# grid barrier: waiters poll the cross-XCD arrival counter directly; SGU unit loads batched up front; plus earlier R1/P8/WT edits
# speedup vs baseline: 1.0277x; 1.0100x over previous
.LBB0_237:
	s_or_b64 exec, exec, s[20:21]
	v_cvt_f32_u32_e32 v4, v2
	s_waitcnt vmcnt(0)
	v_readfirstlane_b32 s3, v3
	v_sub_u32_e32 v3, 0, v2
	v_rcp_iflag_f32_e32 v4, v4
	v_add_u32_e32 v5, s3, v1
	v_mul_f32_e32 v4, 0x4f7ffffe, v4
	v_cvt_u32_f32_e32 v4, v4
	v_mul_lo_u32 v1, v3, v4
	v_mul_hi_u32 v1, v4, v1
	v_add_u32_e32 v1, v4, v1
	v_mul_hi_u32 v1, v5, v1
	v_mul_lo_u32 v3, v1, v2
	v_sub_u32_e32 v3, v5, v3
	v_add_u32_e32 v4, 1, v1
	v_cmp_ge_u32_e32 vcc, v3, v2
	s_nop 1
	v_cndmask_b32_e32 v1, v1, v4, vcc
	v_sub_u32_e32 v4, v3, v2
	v_cndmask_b32_e32 v3, v3, v4, vcc
	v_add_u32_e32 v4, 1, v1
	v_cmp_ge_u32_e32 vcc, v3, v2
	v_add_u32_e32 v3, 1, v5
	s_nop 0
	v_cndmask_b32_e32 v1, v1, v4, vcc
	v_mul_lo_u32 v4, v2, v1
	v_add_u32_e32 v2, v4, v2
	v_cmp_ne_u32_e32 vcc, v3, v2
	s_and_saveexec_b64 s[6:7], vcc
	s_xor_b64 s[6:7], exec, s[6:7]
	s_cbranch_execz .LBB0_251
	s_waitcnt lgkmcnt(0)
	v_add_u32_e32 v3, 1, v1
	v_mul_lo_u32 v3, v3, v0
	v_mov_b32_e32 v0, 0x67000
	global_load_dword v0, v0, s[28:29] offset:1024 sc1
	s_add_u32 s48, s28, 0x67400
	s_addc_u32 s49, s29, 0
	s_waitcnt vmcnt(0)
	v_cmp_lt_u32_e32 vcc, v0, v3
	s_and_saveexec_b64 s[20:21], vcc
	s_cbranch_execz .LBB0_250
	s_add_u32 s46, s28, 0x64200
	s_addc_u32 s47, s29, 0
	s_mov_b32 s3, 1
	s_mov_b64 s[50:51], 0
	v_mov_b32_e32 v0, 0
	s_branch .LBB0_241

.LBB0_243:
	global_load_dword v2, v0, s[48:49] sc1
	s_add_i32 s3, s3, 1
	s_mov_b64 s[58:59], -1
	s_waitcnt vmcnt(0)
	v_cmp_ge_u32_e32 vcc, v2, v3
	s_orn2_b64 s[54:55], vcc, exec
	s_branch .LBB0_240

.LBB0_254:
	s_or_b64 exec, exec, s[20:21]
	v_cvt_f32_u32_e32 v3, v0
	s_waitcnt vmcnt(0)
	v_readfirstlane_b32 s3, v2
	s_add_u32 s20, s28, 0x67500
	s_addc_u32 s21, s29, 0
	v_rcp_iflag_f32_e32 v3, v3
	v_add_u32_e32 v1, s3, v1
	v_add_u32_e32 v4, 1, v1
	s_mov_b64 s[46:47], -1
	v_mul_f32_e32 v2, 0x4f7ffffe, v3
	v_cvt_u32_f32_e32 v2, v2
	v_sub_u32_e32 v3, 0, v0
	v_mul_lo_u32 v3, v3, v2
	v_mul_hi_u32 v3, v2, v3
	v_add_u32_e32 v2, v2, v3
	v_mul_hi_u32 v2, v1, v2
	v_mul_lo_u32 v3, v2, v0
	v_sub_u32_e32 v1, v1, v3
	v_add_u32_e32 v5, 1, v2
	v_cmp_ge_u32_e32 vcc, v1, v0
	v_sub_u32_e32 v3, v1, v0
	s_nop 0
	v_cndmask_b32_e32 v2, v2, v5, vcc
	v_cndmask_b32_e32 v1, v1, v3, vcc
	v_add_u32_e32 v3, 1, v2
	v_cmp_ge_u32_e32 vcc, v1, v0
	s_nop 1
	v_cndmask_b32_e32 v2, v2, v3, vcc
	v_mul_lo_u32 v1, v0, v2
	v_add_u32_e32 v0, v1, v0
	v_cmp_ne_u32_e32 vcc, v4, v0
	v_mov_b32_e32 v5, v0
	v_mov_b64_e32 v[0:1], s[20:21]
	s_and_saveexec_b64 s[6:7], vcc
	s_cbranch_execz .LBB0_266
	v_mov_b32_e32 v0, 0
	global_load_dword v1, v0, s[20:21] offset:-256 sc1
	s_mov_b64 s[50:51], 0
	s_waitcnt vmcnt(0)
	v_cmp_lt_u32_e32 vcc, v1, v5
	s_and_saveexec_b64 s[48:49], vcc
	s_cbranch_execz .LBB0_265
	s_add_u32 s46, s28, 0x64200
	s_addc_u32 s47, s29, 0
	s_mov_b32 s3, 1
	s_branch .LBB0_258

.LBB0_260:
	global_load_dword v1, v0, s[20:21] offset:-256 sc1
	s_add_i32 s3, s3, 1
	s_mov_b64 s[54:55], -1
	s_waitcnt vmcnt(0)
	v_cmp_ge_u32_e32 vcc, v1, v5
	s_orn2_b64 s[60:61], vcc, exec
	s_branch .LBB0_257

.LBB0_364:
	s_or_b64 exec, exec, s[8:9]
	v_cvt_f32_u32_e32 v4, v2
	s_waitcnt vmcnt(0)
	v_readfirstlane_b32 s3, v3
	v_sub_u32_e32 v3, 0, v2
	v_rcp_iflag_f32_e32 v4, v4
	v_add_u32_e32 v5, s3, v1
	v_mul_f32_e32 v4, 0x4f7ffffe, v4
	v_cvt_u32_f32_e32 v4, v4
	v_mul_lo_u32 v1, v3, v4
	v_mul_hi_u32 v1, v4, v1
	v_add_u32_e32 v1, v4, v1
	v_mul_hi_u32 v1, v5, v1
	v_mul_lo_u32 v3, v1, v2
	v_sub_u32_e32 v3, v5, v3
	v_add_u32_e32 v4, 1, v1
	v_cmp_ge_u32_e32 vcc, v3, v2
	s_nop 1
	v_cndmask_b32_e32 v1, v1, v4, vcc
	v_sub_u32_e32 v4, v3, v2
	v_cndmask_b32_e32 v3, v3, v4, vcc
	v_add_u32_e32 v4, 1, v1
	v_cmp_ge_u32_e32 vcc, v3, v2
	v_add_u32_e32 v3, 1, v5
	s_nop 0
	v_cndmask_b32_e32 v1, v1, v4, vcc
	v_mul_lo_u32 v4, v2, v1
	v_add_u32_e32 v2, v4, v2
	v_cmp_ne_u32_e32 vcc, v3, v2
	s_and_saveexec_b64 s[6:7], vcc
	s_xor_b64 s[6:7], exec, s[6:7]
	s_cbranch_execz .LBB0_378
	s_waitcnt lgkmcnt(0)
	v_add_u32_e32 v3, 1, v1
	v_mul_lo_u32 v3, v3, v0
	v_mov_b32_e32 v0, 0x67000
	global_load_dword v0, v0, s[28:29] offset:1024 sc1
	s_add_u32 s12, s28, 0x67400
	s_addc_u32 s13, s29, 0
	s_waitcnt vmcnt(0)
	v_cmp_lt_u32_e32 vcc, v0, v3
	s_and_saveexec_b64 s[8:9], vcc
	s_cbranch_execz .LBB0_377
	s_add_u32 s10, s28, 0x64200
	s_addc_u32 s11, s29, 0
	s_mov_b32 s3, 1
	s_mov_b64 s[14:15], 0
	v_mov_b32_e32 v0, 0
	s_branch .LBB0_368

.LBB0_370:
	global_load_dword v2, v0, s[12:13] sc1
	s_add_i32 s3, s3, 1
	s_mov_b64 s[54:55], -1
	s_waitcnt vmcnt(0)
	v_cmp_ge_u32_e32 vcc, v2, v3
	s_orn2_b64 s[52:53], vcc, exec
	s_branch .LBB0_367

.LBB0_381:
	s_or_b64 exec, exec, s[8:9]
	v_cvt_f32_u32_e32 v3, v0
	s_waitcnt vmcnt(0)
	v_readfirstlane_b32 s3, v2
	s_add_u32 s8, s28, 0x67500
	s_addc_u32 s9, s29, 0
	v_rcp_iflag_f32_e32 v3, v3
	v_add_u32_e32 v1, s3, v1
	v_add_u32_e32 v4, 1, v1
	s_mov_b64 s[10:11], -1
	v_mul_f32_e32 v2, 0x4f7ffffe, v3
	v_cvt_u32_f32_e32 v2, v2
	v_sub_u32_e32 v3, 0, v0
	v_mul_lo_u32 v3, v3, v2
	v_mul_hi_u32 v3, v2, v3
	v_add_u32_e32 v2, v2, v3
	v_mul_hi_u32 v2, v1, v2
	v_mul_lo_u32 v3, v2, v0
	v_sub_u32_e32 v1, v1, v3
	v_add_u32_e32 v5, 1, v2
	v_cmp_ge_u32_e32 vcc, v1, v0
	v_sub_u32_e32 v3, v1, v0
	s_nop 0
	v_cndmask_b32_e32 v2, v2, v5, vcc
	v_cndmask_b32_e32 v1, v1, v3, vcc
	v_add_u32_e32 v3, 1, v2
	v_cmp_ge_u32_e32 vcc, v1, v0
	s_nop 1
	v_cndmask_b32_e32 v2, v2, v3, vcc
	v_mul_lo_u32 v1, v0, v2
	v_add_u32_e32 v0, v1, v0
	v_cmp_ne_u32_e32 vcc, v4, v0
	v_mov_b32_e32 v5, v0
	v_mov_b64_e32 v[0:1], s[8:9]
	s_and_saveexec_b64 s[6:7], vcc
	s_cbranch_execz .LBB0_395
	v_mov_b32_e32 v0, 0
	global_load_dword v1, v0, s[8:9] offset:-256 sc1
	s_mov_b64 s[14:15], 0
	s_waitcnt vmcnt(0)
	v_cmp_lt_u32_e32 vcc, v1, v5
	s_and_saveexec_b64 s[12:13], vcc
	s_cbranch_execz .LBB0_394
	s_add_u32 s10, s28, 0x64200
	s_addc_u32 s11, s29, 0
	s_mov_b32 s3, 1
	s_branch .LBB0_385

.LBB0_387:
	global_load_dword v1, v0, s[8:9] offset:-256 sc1
	s_add_i32 s3, s3, 1
	s_mov_b64 s[52:53], -1
	s_waitcnt vmcnt(0)
	v_cmp_ge_u32_e32 vcc, v1, v5
	s_orn2_b64 s[58:59], vcc, exec
	s_branch .LBB0_384

.LBB0_486:
	global_load_dword v2, v0, s[12:13] sc1
	s_add_i32 s3, s3, 1
	s_mov_b64 s[58:59], -1
	s_waitcnt vmcnt(0)
	v_cmp_ge_u32_e32 vcc, v2, v3
	s_orn2_b64 s[54:55], vcc, exec
	s_branch .LBB0_483

.LBB0_503:
	global_load_dword v1, v0, s[8:9] offset:-256 sc1
	s_add_i32 s3, s3, 1
	s_mov_b64 s[54:55], -1
	s_waitcnt vmcnt(0)
	v_cmp_ge_u32_e32 vcc, v1, v5
	s_orn2_b64 s[60:61], vcc, exec
	s_branch .LBB0_500

.LBB0_660:
	s_or_b64 exec, exec, s[8:9]
	v_cvt_f32_u32_e32 v4, v2
	s_waitcnt vmcnt(0)
	v_readfirstlane_b32 s3, v3
	v_sub_u32_e32 v3, 0, v2
	v_rcp_iflag_f32_e32 v4, v4
	v_add_u32_e32 v5, s3, v1
	v_mul_f32_e32 v4, 0x4f7ffffe, v4
	v_cvt_u32_f32_e32 v4, v4
	v_mul_lo_u32 v1, v3, v4
	v_mul_hi_u32 v1, v4, v1
	v_add_u32_e32 v1, v4, v1
	v_mul_hi_u32 v1, v5, v1
	v_mul_lo_u32 v3, v1, v2
	v_sub_u32_e32 v3, v5, v3
	v_add_u32_e32 v4, 1, v1
	v_cmp_ge_u32_e32 vcc, v3, v2
	s_nop 1
	v_cndmask_b32_e32 v1, v1, v4, vcc
	v_sub_u32_e32 v4, v3, v2
	v_cndmask_b32_e32 v3, v3, v4, vcc
	v_add_u32_e32 v4, 1, v1
	v_cmp_ge_u32_e32 vcc, v3, v2
	v_add_u32_e32 v3, 1, v5
	s_nop 0
	v_cndmask_b32_e32 v1, v1, v4, vcc
	v_mul_lo_u32 v4, v2, v1
	v_add_u32_e32 v2, v4, v2
	v_cmp_ne_u32_e32 vcc, v3, v2
	s_and_saveexec_b64 s[6:7], vcc
	s_xor_b64 s[6:7], exec, s[6:7]
	s_cbranch_execz .LBB0_674
	s_waitcnt lgkmcnt(0)
	v_add_u32_e32 v3, 1, v1
	v_mul_lo_u32 v3, v3, v0
	v_mov_b32_e32 v0, 0x67000
	global_load_dword v0, v0, s[28:29] offset:1024 sc1
	s_add_u32 s12, s28, 0x67400
	s_addc_u32 s13, s29, 0
	s_waitcnt vmcnt(0)
	v_cmp_lt_u32_e32 vcc, v0, v3
	s_and_saveexec_b64 s[8:9], vcc
	s_cbranch_execz .LBB0_673
	s_add_u32 s10, s28, 0x64200
	s_addc_u32 s11, s29, 0
	s_mov_b32 s3, 1
	s_mov_b64 s[60:61], 0
	v_mov_b32_e32 v0, 0
	s_branch .LBB0_664

.LBB0_666:
	global_load_dword v2, v0, s[12:13] sc1
	s_add_i32 s3, s3, 1
	s_mov_b64 s[68:69], -1
	s_waitcnt vmcnt(0)
	v_cmp_ge_u32_e32 vcc, v2, v3
	s_orn2_b64 s[64:65], vcc, exec
	s_branch .LBB0_663

.LBB0_677:
	s_or_b64 exec, exec, s[8:9]
	v_cvt_f32_u32_e32 v3, v0
	s_waitcnt vmcnt(0)
	v_readfirstlane_b32 s3, v2
	s_add_u32 s8, s28, 0x67500
	s_addc_u32 s9, s29, 0
	v_rcp_iflag_f32_e32 v3, v3
	v_add_u32_e32 v1, s3, v1
	v_add_u32_e32 v4, 1, v1
	s_mov_b64 s[10:11], -1
	v_mul_f32_e32 v2, 0x4f7ffffe, v3
	v_cvt_u32_f32_e32 v2, v2
	v_sub_u32_e32 v3, 0, v0
	v_mul_lo_u32 v3, v3, v2
	v_mul_hi_u32 v3, v2, v3
	v_add_u32_e32 v2, v2, v3
	v_mul_hi_u32 v2, v1, v2
	v_mul_lo_u32 v3, v2, v0
	v_sub_u32_e32 v1, v1, v3
	v_add_u32_e32 v5, 1, v2
	v_cmp_ge_u32_e32 vcc, v1, v0
	v_sub_u32_e32 v3, v1, v0
	s_nop 0
	v_cndmask_b32_e32 v2, v2, v5, vcc
	v_cndmask_b32_e32 v1, v1, v3, vcc
	v_add_u32_e32 v3, 1, v2
	v_cmp_ge_u32_e32 vcc, v1, v0
	s_nop 1
	v_cndmask_b32_e32 v2, v2, v3, vcc
	v_mul_lo_u32 v1, v0, v2
	v_add_u32_e32 v0, v1, v0
	v_cmp_ne_u32_e32 vcc, v4, v0
	v_mov_b32_e32 v5, v0
	v_mov_b64_e32 v[0:1], s[8:9]
	s_and_saveexec_b64 s[6:7], vcc
	s_cbranch_execz .LBB0_689
	v_mov_b32_e32 v0, 0
	global_load_dword v1, v0, s[8:9] offset:-256 sc1
	s_mov_b64 s[60:61], 0
	s_waitcnt vmcnt(0)
	v_cmp_lt_u32_e32 vcc, v1, v5
	s_and_saveexec_b64 s[12:13], vcc
	s_cbranch_execz .LBB0_688
	s_add_u32 s10, s28, 0x64200
	s_addc_u32 s11, s29, 0
	s_mov_b32 s3, 1
	s_branch .LBB0_681

.LBB0_683:
	global_load_dword v1, v0, s[8:9] offset:-256 sc1
	s_add_i32 s3, s3, 1
	s_mov_b64 s[64:65], -1
	s_waitcnt vmcnt(0)
	v_cmp_ge_u32_e32 vcc, v1, v5
	s_orn2_b64 s[70:71], vcc, exec
	s_branch .LBB0_680

.LBB0_696:
	s_and_b32 s6, s3, 0xffffff80
	s_and_b32 s0, s13, 3
	v_add_u32_e32 v0, s6, v96
	s_mov_b32 s1, s9
	s_lshl_b32 s8, s0, 9
	s_lshl_b32 s4, s0, 10
	v_add_u32_e32 v6, s6, v97
	v_add_u32_e32 v8, s6, v98
	v_add_u32_e32 v10, s6, v99
	v_add_u32_e32 v12, s6, v100
	v_add_u32_e32 v14, s6, v101
	v_add_u32_e32 v16, s6, v102
	v_add_u32_e32 v34, s6, v103
	s_lshl_b32 s0, s0, 7
	v_ashrrev_i32_e32 v1, 31, v0
	s_mov_b32 s5, s9
	v_ashrrev_i32_e32 v7, 31, v6
	v_ashrrev_i32_e32 v9, 31, v8
	v_ashrrev_i32_e32 v11, 31, v10
	v_ashrrev_i32_e32 v13, 31, v12
	v_ashrrev_i32_e32 v15, 31, v14
	v_ashrrev_i32_e32 v17, 31, v16
	v_ashrrev_i32_e32 v35, 31, v34
	v_lshl_add_u64 v[38:39], s[0:1], 0, v[84:85]
	v_lshlrev_b64 v[40:41], 11, v[0:1]
	v_lshlrev_b64 v[0:1], 2, v[0:1]
	v_lshl_add_u64 v[36:37], v[78:79], 0, s[8:9]
	v_lshl_add_u64 v[2:3], v[80:81], 0, s[4:5]
	v_lshlrev_b64 v[42:43], 11, v[6:7]
	v_lshlrev_b64 v[6:7], 2, v[6:7]
	v_lshlrev_b64 v[44:45], 11, v[8:9]
	v_lshlrev_b64 v[8:9], 2, v[8:9]
	v_lshlrev_b64 v[46:47], 11, v[10:11]
	v_lshlrev_b64 v[10:11], 2, v[10:11]
	v_lshlrev_b64 v[48:49], 11, v[12:13]
	v_lshlrev_b64 v[12:13], 2, v[12:13]
	v_lshlrev_b64 v[50:51], 11, v[14:15]
	v_lshlrev_b64 v[52:53], 11, v[16:17]
	v_lshlrev_b64 v[54:55], 11, v[34:35]
	v_lshlrev_b64 v[34:35], 2, v[34:35]
	v_lshlrev_b64 v[38:39], 9, v[38:39]
	v_lshl_add_u64 v[56:57], s[52:53], 0, v[0:1]
	s_barrier
	v_lshl_add_u64 v[4:5], v[82:83], 0, s[4:5]
	global_load_dwordx4 v[148:151], v[2:3], off offset:16
	global_load_dwordx4 v[144:147], v[2:3], off
	global_load_dwordx4 v[156:159], v[4:5], off offset:16
	global_load_dwordx4 v[152:155], v[4:5], off
	v_lshl_add_u64 v[40:41], v[36:37], 0, v[40:41]
	v_lshl_add_u64 v[58:59], s[14:15], 0, v[0:1]
	v_lshl_add_u64 v[42:43], v[36:37], 0, v[42:43]
	v_lshl_add_u64 v[60:61], s[52:53], 0, v[6:7]
	v_lshl_add_u64 v[62:63], s[14:15], 0, v[6:7]
	v_lshl_add_u64 v[44:45], v[36:37], 0, v[44:45]
	v_lshl_add_u64 v[64:65], s[52:53], 0, v[8:9]
	v_lshl_add_u64 v[66:67], s[14:15], 0, v[8:9]
	v_lshl_add_u64 v[46:47], v[36:37], 0, v[46:47]
	v_lshl_add_u64 v[68:69], s[52:53], 0, v[10:11]
	v_lshl_add_u64 v[70:71], s[14:15], 0, v[10:11]
	v_lshl_add_u64 v[48:49], v[36:37], 0, v[48:49]
	v_lshl_add_u64 v[72:73], s[52:53], 0, v[12:13]
	v_lshl_add_u64 v[74:75], s[14:15], 0, v[12:13]
	v_lshl_add_u64 v[50:51], v[36:37], 0, v[50:51]
	v_lshl_add_u64 v[12:13], v[36:37], 0, v[52:53]
	v_lshl_add_u64 v[6:7], v[36:37], 0, v[54:55]
	v_lshl_add_u64 v[8:9], s[52:53], 0, v[34:35]
	v_lshl_add_u64 v[10:11], s[14:15], 0, v[34:35]
	v_lshl_add_u64 v[0:1], v[86:87], 0, v[38:39]
	v_lshlrev_b64 v[14:15], 2, v[14:15]
	v_lshl_add_u64 v[90:91], s[52:53], 0, v[14:15]
	v_lshl_add_u64 v[92:93], s[14:15], 0, v[14:15]
	v_lshlrev_b64 v[16:17], 2, v[16:17]
	v_lshl_add_u64 v[14:15], s[52:53], 0, v[16:17]
	v_lshl_add_u64 v[16:17], s[14:15], 0, v[16:17]
	s_add_i32 s3, s3, s11
	global_load_dword v193, v[56:57], off
	global_load_dword v192, v[58:59], off
	global_load_dwordx4 v[160:163], v[40:41], off
	global_load_dword v195, v[60:61], off
	global_load_dword v194, v[62:63], off
	global_load_dwordx4 v[164:167], v[42:43], off
	global_load_dword v197, v[64:65], off
	global_load_dword v196, v[66:67], off
	global_load_dwordx4 v[168:171], v[44:45], off
	global_load_dword v199, v[68:69], off
	global_load_dword v198, v[70:71], off
	global_load_dwordx4 v[172:175], v[46:47], off
	global_load_dword v201, v[72:73], off
	global_load_dword v200, v[74:75], off
	global_load_dwordx4 v[176:179], v[48:49], off
	global_load_dword v203, v[90:91], off
	global_load_dword v202, v[92:93], off
	global_load_dwordx4 v[180:183], v[50:51], off
	global_load_dword v205, v[14:15], off
	global_load_dword v204, v[16:17], off
	global_load_dwordx4 v[184:187], v[12:13], off
	global_load_dword v207, v[8:9], off
	global_load_dword v206, v[10:11], off
	global_load_dwordx4 v[188:191], v[6:7], off
	global_load_dwordx4 v[208:211], v[0:1], off
	global_load_dwordx4 v[212:215], v[0:1], off offset:64
	global_load_dwordx4 v[216:219], v[0:1], off offset:128
	global_load_dwordx4 v[220:223], v[0:1], off offset:192
	global_load_dwordx4 v[224:227], v[0:1], off offset:256
	global_load_dwordx4 v[232:235], v[0:1], off offset:320
	global_load_dwordx4 v[236:239], v[0:1], off offset:384
	global_load_dwordx4 v[240:243], v[0:1], off offset:448
	s_waitcnt vmcnt(29)
	v_pk_mul_f32 v[192:193], v[192:193], s[10:11] op_sel_hi:[1,0]
	s_nop 0
	v_fma_f32 v192, -v193, v193, v192
	v_add_f32_e32 v192, 0x358637bd, v192
	v_rsq_f32_e32 v192, v192
	v_lshlrev_b32_e32 v22, 16, v160
	v_and_b32_e32 v23, 0xffff0000, v160
	v_lshlrev_b32_e32 v24, 16, v161
	v_and_b32_e32 v25, 0xffff0000, v161
	v_lshlrev_b32_e32 v26, 16, v162
	v_and_b32_e32 v27, 0xffff0000, v162
	v_lshlrev_b32_e32 v28, 16, v163
	v_and_b32_e32 v29, 0xffff0000, v163
	v_sub_f32_e32 v22, v22, v193
	v_sub_f32_e32 v23, v23, v193
	v_sub_f32_e32 v24, v24, v193
	v_sub_f32_e32 v25, v25, v193
	v_sub_f32_e32 v26, v26, v193
	v_sub_f32_e32 v27, v27, v193
	v_sub_f32_e32 v28, v28, v193
	v_sub_f32_e32 v29, v29, v193
	v_mul_f32_e32 v22, v22, v192
	v_mul_f32_e32 v23, v23, v192
	v_mul_f32_e32 v24, v24, v192
	v_mul_f32_e32 v25, v25, v192
	v_mul_f32_e32 v26, v26, v192
	v_mul_f32_e32 v27, v27, v192
	v_mul_f32_e32 v28, v28, v192
	v_mul_f32_e32 v29, v29, v192
	v_fma_f32 v22, v144, v22, v152
	v_fma_f32 v23, v145, v23, v153
	v_fma_f32 v24, v146, v24, v154
	v_fma_f32 v25, v147, v25, v155
	v_fma_f32 v26, v148, v26, v156
	v_fma_f32 v27, v149, v27, v157
	v_fma_f32 v28, v150, v28, v158
	v_fma_f32 v29, v151, v29, v159
	v_cvt_pk_bf16_f32 v18, v22, v23
	v_cvt_pk_bf16_f32 v19, v24, v25
	v_cvt_pk_bf16_f32 v20, v26, v27
	v_cvt_pk_bf16_f32 v21, v28, v29
	ds_write_b128 v105, v[18:21]
	s_waitcnt vmcnt(26)
	v_pk_mul_f32 v[194:195], v[194:195], s[10:11] op_sel_hi:[1,0]
	s_nop 0
	v_fma_f32 v194, -v195, v195, v194
	v_add_f32_e32 v194, 0x358637bd, v194
	v_rsq_f32_e32 v194, v194
	v_lshlrev_b32_e32 v22, 16, v164
	v_and_b32_e32 v23, 0xffff0000, v164
	v_lshlrev_b32_e32 v24, 16, v165
	v_and_b32_e32 v25, 0xffff0000, v165
	v_lshlrev_b32_e32 v26, 16, v166
	v_and_b32_e32 v27, 0xffff0000, v166
	v_lshlrev_b32_e32 v28, 16, v167
	v_and_b32_e32 v29, 0xffff0000, v167
	v_sub_f32_e32 v22, v22, v195
	v_sub_f32_e32 v23, v23, v195
	v_sub_f32_e32 v24, v24, v195
	v_sub_f32_e32 v25, v25, v195
	v_sub_f32_e32 v26, v26, v195
	v_sub_f32_e32 v27, v27, v195
	v_sub_f32_e32 v28, v28, v195
	v_sub_f32_e32 v29, v29, v195
	v_mul_f32_e32 v22, v22, v194
	v_mul_f32_e32 v23, v23, v194
	v_mul_f32_e32 v24, v24, v194
	v_mul_f32_e32 v25, v25, v194
	v_mul_f32_e32 v26, v26, v194
	v_mul_f32_e32 v27, v27, v194
	v_mul_f32_e32 v28, v28, v194
	v_mul_f32_e32 v29, v29, v194
	v_fma_f32 v22, v144, v22, v152
	v_fma_f32 v23, v145, v23, v153
	v_fma_f32 v24, v146, v24, v154
	v_fma_f32 v25, v147, v25, v155
	v_fma_f32 v26, v148, v26, v156
	v_fma_f32 v27, v149, v27, v157
	v_fma_f32 v28, v150, v28, v158
	v_fma_f32 v29, v151, v29, v159
	v_cvt_pk_bf16_f32 v30, v22, v23
	v_cvt_pk_bf16_f32 v31, v24, v25
	v_cvt_pk_bf16_f32 v32, v26, v27
	v_cvt_pk_bf16_f32 v33, v28, v29
	ds_write_b128 v106, v[30:33]
	s_waitcnt vmcnt(23)
	v_pk_mul_f32 v[196:197], v[196:197], s[10:11] op_sel_hi:[1,0]
	s_nop 0
	v_fma_f32 v196, -v197, v197, v196
	v_add_f32_e32 v196, 0x358637bd, v196
	v_rsq_f32_e32 v196, v196
	v_lshlrev_b32_e32 v22, 16, v168
	v_and_b32_e32 v23, 0xffff0000, v168
	v_lshlrev_b32_e32 v24, 16, v169
	v_and_b32_e32 v25, 0xffff0000, v169
	v_lshlrev_b32_e32 v26, 16, v170
	v_and_b32_e32 v27, 0xffff0000, v170
	v_lshlrev_b32_e32 v28, 16, v171
	v_and_b32_e32 v29, 0xffff0000, v171
	v_sub_f32_e32 v22, v22, v197
	v_sub_f32_e32 v23, v23, v197
	v_sub_f32_e32 v24, v24, v197
	v_sub_f32_e32 v25, v25, v197
	v_sub_f32_e32 v26, v26, v197
	v_sub_f32_e32 v27, v27, v197
	v_sub_f32_e32 v28, v28, v197
	v_sub_f32_e32 v29, v29, v197
	v_mul_f32_e32 v22, v22, v196
	v_mul_f32_e32 v23, v23, v196
	v_mul_f32_e32 v24, v24, v196
	v_mul_f32_e32 v25, v25, v196
	v_mul_f32_e32 v26, v26, v196
	v_mul_f32_e32 v27, v27, v196
	v_mul_f32_e32 v28, v28, v196
	v_mul_f32_e32 v29, v29, v196
	v_fma_f32 v22, v144, v22, v152
	v_fma_f32 v23, v145, v23, v153
	v_fma_f32 v24, v146, v24, v154
	v_fma_f32 v25, v147, v25, v155
	v_fma_f32 v26, v148, v26, v156
	v_fma_f32 v27, v149, v27, v157
	v_fma_f32 v28, v150, v28, v158
	v_fma_f32 v29, v151, v29, v159
	v_cvt_pk_bf16_f32 v18, v22, v23
	v_cvt_pk_bf16_f32 v19, v24, v25
	v_cvt_pk_bf16_f32 v20, v26, v27
	v_cvt_pk_bf16_f32 v21, v28, v29
	ds_write_b128 v107, v[18:21]
	s_waitcnt vmcnt(20)
	v_pk_mul_f32 v[198:199], v[198:199], s[10:11] op_sel_hi:[1,0]
	s_nop 0
	v_fma_f32 v198, -v199, v199, v198
	v_add_f32_e32 v198, 0x358637bd, v198
	v_rsq_f32_e32 v198, v198
	v_lshlrev_b32_e32 v22, 16, v172
	v_and_b32_e32 v23, 0xffff0000, v172
	v_lshlrev_b32_e32 v24, 16, v173
	v_and_b32_e32 v25, 0xffff0000, v173
	v_lshlrev_b32_e32 v26, 16, v174
	v_and_b32_e32 v27, 0xffff0000, v174
	v_lshlrev_b32_e32 v28, 16, v175
	v_and_b32_e32 v29, 0xffff0000, v175
	v_sub_f32_e32 v22, v22, v199
	v_sub_f32_e32 v23, v23, v199
	v_sub_f32_e32 v24, v24, v199
	v_sub_f32_e32 v25, v25, v199
	v_sub_f32_e32 v26, v26, v199
	v_sub_f32_e32 v27, v27, v199
	v_sub_f32_e32 v28, v28, v199
	v_sub_f32_e32 v29, v29, v199
	v_mul_f32_e32 v22, v22, v198
	v_mul_f32_e32 v23, v23, v198
	v_mul_f32_e32 v24, v24, v198
	v_mul_f32_e32 v25, v25, v198
	v_mul_f32_e32 v26, v26, v198
	v_mul_f32_e32 v27, v27, v198
	v_mul_f32_e32 v28, v28, v198
	v_mul_f32_e32 v29, v29, v198
	v_fma_f32 v22, v144, v22, v152
	v_fma_f32 v23, v145, v23, v153
	v_fma_f32 v24, v146, v24, v154
	v_fma_f32 v25, v147, v25, v155
	v_fma_f32 v26, v148, v26, v156
	v_fma_f32 v27, v149, v27, v157
	v_fma_f32 v28, v150, v28, v158
	v_fma_f32 v29, v151, v29, v159
	v_cvt_pk_bf16_f32 v30, v22, v23
	v_cvt_pk_bf16_f32 v31, v24, v25
	v_cvt_pk_bf16_f32 v32, v26, v27
	v_cvt_pk_bf16_f32 v33, v28, v29
	ds_write_b128 v108, v[30:33]
	s_waitcnt vmcnt(17)
	v_pk_mul_f32 v[200:201], v[200:201], s[10:11] op_sel_hi:[1,0]
	s_nop 0
	v_fma_f32 v200, -v201, v201, v200
	v_add_f32_e32 v200, 0x358637bd, v200
	v_rsq_f32_e32 v200, v200
	v_lshlrev_b32_e32 v22, 16, v176
	v_and_b32_e32 v23, 0xffff0000, v176
	v_lshlrev_b32_e32 v24, 16, v177
	v_and_b32_e32 v25, 0xffff0000, v177
	v_lshlrev_b32_e32 v26, 16, v178
	v_and_b32_e32 v27, 0xffff0000, v178
	v_lshlrev_b32_e32 v28, 16, v179
	v_and_b32_e32 v29, 0xffff0000, v179
	v_sub_f32_e32 v22, v22, v201
	v_sub_f32_e32 v23, v23, v201
	v_sub_f32_e32 v24, v24, v201
	v_sub_f32_e32 v25, v25, v201
	v_sub_f32_e32 v26, v26, v201
	v_sub_f32_e32 v27, v27, v201
	v_sub_f32_e32 v28, v28, v201
	v_sub_f32_e32 v29, v29, v201
	v_mul_f32_e32 v22, v22, v200
	v_mul_f32_e32 v23, v23, v200
	v_mul_f32_e32 v24, v24, v200
	v_mul_f32_e32 v25, v25, v200
	v_mul_f32_e32 v26, v26, v200
	v_mul_f32_e32 v27, v27, v200
	v_mul_f32_e32 v28, v28, v200
	v_mul_f32_e32 v29, v29, v200
	v_fma_f32 v22, v144, v22, v152
	v_fma_f32 v23, v145, v23, v153
	v_fma_f32 v24, v146, v24, v154
	v_fma_f32 v25, v147, v25, v155
	v_fma_f32 v26, v148, v26, v156
	v_fma_f32 v27, v149, v27, v157
	v_fma_f32 v28, v150, v28, v158
	v_fma_f32 v29, v151, v29, v159
	v_cvt_pk_bf16_f32 v18, v22, v23
	v_cvt_pk_bf16_f32 v19, v24, v25
	v_cvt_pk_bf16_f32 v20, v26, v27
	v_cvt_pk_bf16_f32 v21, v28, v29
	ds_write_b128 v109, v[18:21]
	s_waitcnt vmcnt(14)
	v_pk_mul_f32 v[202:203], v[202:203], s[10:11] op_sel_hi:[1,0]
	s_nop 0
	v_fma_f32 v202, -v203, v203, v202
	v_add_f32_e32 v202, 0x358637bd, v202
	v_rsq_f32_e32 v202, v202
	v_lshlrev_b32_e32 v22, 16, v180
	v_and_b32_e32 v23, 0xffff0000, v180
	v_lshlrev_b32_e32 v24, 16, v181
	v_and_b32_e32 v25, 0xffff0000, v181
	v_lshlrev_b32_e32 v26, 16, v182
	v_and_b32_e32 v27, 0xffff0000, v182
	v_lshlrev_b32_e32 v28, 16, v183
	v_and_b32_e32 v29, 0xffff0000, v183
	v_sub_f32_e32 v22, v22, v203
	v_sub_f32_e32 v23, v23, v203
	v_sub_f32_e32 v24, v24, v203
	v_sub_f32_e32 v25, v25, v203
	v_sub_f32_e32 v26, v26, v203
	v_sub_f32_e32 v27, v27, v203
	v_sub_f32_e32 v28, v28, v203
	v_sub_f32_e32 v29, v29, v203
	v_mul_f32_e32 v22, v22, v202
	v_mul_f32_e32 v23, v23, v202
	v_mul_f32_e32 v24, v24, v202
	v_mul_f32_e32 v25, v25, v202
	v_mul_f32_e32 v26, v26, v202
	v_mul_f32_e32 v27, v27, v202
	v_mul_f32_e32 v28, v28, v202
	v_mul_f32_e32 v29, v29, v202
	v_fma_f32 v22, v144, v22, v152
	v_fma_f32 v23, v145, v23, v153
	v_fma_f32 v24, v146, v24, v154
	v_fma_f32 v25, v147, v25, v155
	v_fma_f32 v26, v148, v26, v156
	v_fma_f32 v27, v149, v27, v157
	v_fma_f32 v28, v150, v28, v158
	v_fma_f32 v29, v151, v29, v159
	v_cvt_pk_bf16_f32 v30, v22, v23
	v_cvt_pk_bf16_f32 v31, v24, v25
	v_cvt_pk_bf16_f32 v32, v26, v27
	v_cvt_pk_bf16_f32 v33, v28, v29
	ds_write_b128 v110, v[30:33]
	s_waitcnt vmcnt(11)
	v_pk_mul_f32 v[204:205], v[204:205], s[10:11] op_sel_hi:[1,0]
	s_nop 0
	v_fma_f32 v204, -v205, v205, v204
	v_add_f32_e32 v204, 0x358637bd, v204
	v_rsq_f32_e32 v204, v204
	v_lshlrev_b32_e32 v22, 16, v184
	v_and_b32_e32 v23, 0xffff0000, v184
	v_lshlrev_b32_e32 v24, 16, v185
	v_and_b32_e32 v25, 0xffff0000, v185
	v_lshlrev_b32_e32 v26, 16, v186
	v_and_b32_e32 v27, 0xffff0000, v186
	v_lshlrev_b32_e32 v28, 16, v187
	v_and_b32_e32 v29, 0xffff0000, v187
	v_sub_f32_e32 v22, v22, v205
	v_sub_f32_e32 v23, v23, v205
	v_sub_f32_e32 v24, v24, v205
	v_sub_f32_e32 v25, v25, v205
	v_sub_f32_e32 v26, v26, v205
	v_sub_f32_e32 v27, v27, v205
	v_sub_f32_e32 v28, v28, v205
	v_sub_f32_e32 v29, v29, v205
	v_mul_f32_e32 v22, v22, v204
	v_mul_f32_e32 v23, v23, v204
	v_mul_f32_e32 v24, v24, v204
	v_mul_f32_e32 v25, v25, v204
	v_mul_f32_e32 v26, v26, v204
	v_mul_f32_e32 v27, v27, v204
	v_mul_f32_e32 v28, v28, v204
	v_mul_f32_e32 v29, v29, v204
	v_fma_f32 v22, v144, v22, v152
	v_fma_f32 v23, v145, v23, v153
	v_fma_f32 v24, v146, v24, v154
	v_fma_f32 v25, v147, v25, v155
	v_fma_f32 v26, v148, v26, v156
	v_fma_f32 v27, v149, v27, v157
	v_fma_f32 v28, v150, v28, v158
	v_fma_f32 v29, v151, v29, v159
	v_cvt_pk_bf16_f32 v18, v22, v23
	v_cvt_pk_bf16_f32 v19, v24, v25
	v_cvt_pk_bf16_f32 v20, v26, v27
	v_cvt_pk_bf16_f32 v21, v28, v29
	ds_write_b128 v111, v[18:21]
	s_waitcnt vmcnt(8)
	v_pk_mul_f32 v[206:207], v[206:207], s[10:11] op_sel_hi:[1,0]
	s_nop 0
	v_fma_f32 v206, -v207, v207, v206
	v_add_f32_e32 v206, 0x358637bd, v206
	v_rsq_f32_e32 v206, v206
	v_lshlrev_b32_e32 v22, 16, v188
	v_and_b32_e32 v23, 0xffff0000, v188
	v_lshlrev_b32_e32 v24, 16, v189
	v_and_b32_e32 v25, 0xffff0000, v189
	v_lshlrev_b32_e32 v26, 16, v190
	v_and_b32_e32 v27, 0xffff0000, v190
	v_lshlrev_b32_e32 v28, 16, v191
	v_and_b32_e32 v29, 0xffff0000, v191
	v_sub_f32_e32 v22, v22, v207
	v_sub_f32_e32 v23, v23, v207
	v_sub_f32_e32 v24, v24, v207
	v_sub_f32_e32 v25, v25, v207
	v_sub_f32_e32 v26, v26, v207
	v_sub_f32_e32 v27, v27, v207
	v_sub_f32_e32 v28, v28, v207
	v_sub_f32_e32 v29, v29, v207
	v_mul_f32_e32 v22, v22, v206
	v_mul_f32_e32 v23, v23, v206
	v_mul_f32_e32 v24, v24, v206
	v_mul_f32_e32 v25, v25, v206
	v_mul_f32_e32 v26, v26, v206
	v_mul_f32_e32 v27, v27, v206
	v_mul_f32_e32 v28, v28, v206
	v_mul_f32_e32 v29, v29, v206
	v_fma_f32 v22, v144, v22, v152
	v_fma_f32 v23, v145, v23, v153
	v_fma_f32 v24, v146, v24, v154
	v_fma_f32 v25, v147, v25, v155
	v_fma_f32 v26, v148, v26, v156
	v_fma_f32 v27, v149, v27, v157
	v_fma_f32 v28, v150, v28, v158
	v_fma_f32 v29, v151, v29, v159
	v_cvt_pk_bf16_f32 v30, v22, v23
	v_cvt_pk_bf16_f32 v31, v24, v25
	v_cvt_pk_bf16_f32 v32, v26, v27
	v_cvt_pk_bf16_f32 v33, v28, v29
	ds_write_b128 v112, v[30:33]
	s_waitcnt lgkmcnt(0)
	s_barrier
	v_add_u32_e32 v244, s6, v84
	v_ashrrev_i32_e32 v245, 31, v244
	v_lshlrev_b64 v[244:245], 11, v[244:245]
	v_lshl_add_u64 v[244:245], s[46:47], 0, v[244:245]
	v_lshl_add_u64 v[244:245], v[244:245], 0, s[8:9]
	v_lshl_add_u64 v[244:245], v[244:245], 0, v[76:77]
	global_load_dwordx2 v[144:145], v[244:245], off
	global_load_dwordx2 v[146:147], v[244:245], off offset:32
	global_load_dwordx2 v[148:149], v[244:245], off offset:64
	global_load_dwordx2 v[150:151], v[244:245], off offset:96
	global_load_dwordx2 v[152:153], v[244:245], off offset:128
	global_load_dwordx2 v[154:155], v[244:245], off offset:160
	global_load_dwordx2 v[156:157], v[244:245], off offset:192
	global_load_dwordx2 v[158:159], v[244:245], off offset:224
	global_load_dwordx2 v[160:161], v[244:245], off offset:256
	global_load_dwordx2 v[162:163], v[244:245], off offset:288
	global_load_dwordx2 v[164:165], v[244:245], off offset:320
	global_load_dwordx2 v[166:167], v[244:245], off offset:352
	global_load_dwordx2 v[168:169], v[244:245], off offset:384
	global_load_dwordx2 v[170:171], v[244:245], off offset:416
	global_load_dwordx2 v[172:173], v[244:245], off offset:448
	global_load_dwordx2 v[174:175], v[244:245], off offset:480
	v_add_u32_e32 v246, s0, v84
	v_ashrrev_i32_e32 v247, 31, v246
	v_lshl_add_u64 v[246:247], v[246:247], 2, s[42:43]
	global_load_dword v113, v[246:247], off
	s_waitcnt vmcnt(17)
	v_cvt_pk_bf16_f32 v12, v208, v209
	v_cvt_pk_bf16_f32 v13, v210, v211
	v_cvt_pk_bf16_f32 v14, v212, v213
	v_cvt_pk_bf16_f32 v15, v214, v215
	v_cvt_pk_bf16_f32 v8, v216, v217
	v_cvt_pk_bf16_f32 v9, v218, v219
	v_cvt_pk_bf16_f32 v10, v220, v221
	v_cvt_pk_bf16_f32 v11, v222, v223
	v_cvt_pk_bf16_f32 v4, v224, v225
	v_cvt_pk_bf16_f32 v5, v226, v227
	v_cvt_pk_bf16_f32 v6, v232, v233
	v_cvt_pk_bf16_f32 v7, v234, v235
	v_cvt_pk_bf16_f32 v0, v236, v237
	v_cvt_pk_bf16_f32 v1, v238, v239
	v_cvt_pk_bf16_f32 v2, v240, v241
	v_cvt_pk_bf16_f32 v3, v242, v243
	ds_read_b64_tr_b16 v[16:17], v104
	ds_read_b64_tr_b16 v[18:19], v104 offset:8704
	ds_read_b64_tr_b16 v[22:23], v104 offset:8736
	ds_read_b64_tr_b16 v[20:21], v104 offset:32
	ds_read_b64_tr_b16 v[24:25], v104 offset:64
	ds_read_b64_tr_b16 v[28:29], v104 offset:96
	ds_read_b64_tr_b16 v[26:27], v104 offset:8768
	ds_read_b64_tr_b16 v[30:31], v104 offset:8800
	ds_read_b64_tr_b16 v[32:33], v104 offset:128
	ds_read_b64_tr_b16 v[34:35], v104 offset:8832
	ds_read_b64_tr_b16 v[38:39], v104 offset:8864
	ds_read_b64_tr_b16 v[36:37], v104 offset:160
	ds_read_b64_tr_b16 v[40:41], v104 offset:192
	ds_read_b64_tr_b16 v[44:45], v104 offset:224
	ds_read_b64_tr_b16 v[42:43], v104 offset:8896
	ds_read_b64_tr_b16 v[46:47], v104 offset:8928
	ds_read_b64_tr_b16 v[48:49], v104 offset:256
	ds_read_b64_tr_b16 v[50:51], v104 offset:8960
	ds_read_b64_tr_b16 v[54:55], v104 offset:8992
	ds_read_b64_tr_b16 v[52:53], v104 offset:288
	ds_read_b64_tr_b16 v[56:57], v104 offset:320
	ds_read_b64_tr_b16 v[60:61], v104 offset:352
	ds_read_b64_tr_b16 v[58:59], v104 offset:9024
	ds_read_b64_tr_b16 v[62:63], v104 offset:9056
	ds_read_b64_tr_b16 v[64:65], v104 offset:384
	ds_read_b64_tr_b16 v[66:67], v104 offset:9088
	ds_read_b64_tr_b16 v[70:71], v104 offset:9120
	ds_read_b64_tr_b16 v[68:69], v104 offset:416
	ds_read_b64_tr_b16 v[72:73], v104 offset:448
	ds_read_b64_tr_b16 v[90:91], v104 offset:480
	ds_read_b64_tr_b16 v[74:75], v104 offset:9152
	ds_read_b64_tr_b16 v[92:93], v104 offset:9184
	ds_read_b64_tr_b16 v[114:115], v104 offset:17408
	ds_read_b64_tr_b16 v[116:117], v104 offset:26112
	s_waitcnt lgkmcnt(14)
	v_mfma_f32_16x16x32_bf16 v[16:19], v[16:19], v[12:15], 0
	ds_read_b64_tr_b16 v[120:121], v104 offset:26144
	ds_read_b64_tr_b16 v[118:119], v104 offset:17440
	ds_read_b64_tr_b16 v[122:123], v104 offset:17472
	v_mfma_f32_16x16x32_bf16 v[20:23], v[20:23], v[12:15], 0
	v_mfma_f32_16x16x32_bf16 v[24:27], v[24:27], v[12:15], 0
	v_mfma_f32_16x16x32_bf16 v[28:31], v[28:31], v[12:15], 0
	v_mfma_f32_16x16x32_bf16 v[32:35], v[32:35], v[12:15], 0
	v_mfma_f32_16x16x32_bf16 v[36:39], v[36:39], v[12:15], 0
	v_mfma_f32_16x16x32_bf16 v[40:43], v[40:43], v[12:15], 0
	v_mfma_f32_16x16x32_bf16 v[44:47], v[44:47], v[12:15], 0
	v_mfma_f32_16x16x32_bf16 v[48:51], v[48:51], v[12:15], 0
	v_mfma_f32_16x16x32_bf16 v[52:55], v[52:55], v[12:15], 0
	s_waitcnt lgkmcnt(14)
	v_mfma_f32_16x16x32_bf16 v[56:59], v[56:59], v[12:15], 0
	s_waitcnt lgkmcnt(13)
	v_mfma_f32_16x16x32_bf16 v[60:63], v[60:63], v[12:15], 0
	s_waitcnt lgkmcnt(11)
	v_mfma_f32_16x16x32_bf16 v[64:67], v[64:67], v[12:15], 0
	s_waitcnt lgkmcnt(9)
	v_mfma_f32_16x16x32_bf16 v[68:71], v[68:71], v[12:15], 0
	s_waitcnt lgkmcnt(6)
	v_mfma_f32_16x16x32_bf16 v[72:75], v[72:75], v[12:15], 0
	s_waitcnt lgkmcnt(5)
	v_mfma_f32_16x16x32_bf16 v[12:15], v[90:93], v[12:15], 0
	ds_read_b64_tr_b16 v[90:91], v104 offset:17504
	ds_read_b64_tr_b16 v[124:125], v104 offset:26176
	ds_read_b64_tr_b16 v[92:93], v104 offset:26208
	s_waitcnt lgkmcnt(6)
	v_mfma_f32_16x16x32_bf16 v[16:19], v[114:117], v[8:11], v[16:19]
	ds_read_b64_tr_b16 v[114:115], v104 offset:17536
	ds_read_b64_tr_b16 v[116:117], v104 offset:26240
	s_waitcnt lgkmcnt(6)
	v_mfma_f32_16x16x32_bf16 v[20:23], v[118:121], v[8:11], v[20:23]
	s_waitcnt lgkmcnt(3)
	v_mfma_f32_16x16x32_bf16 v[24:27], v[122:125], v[8:11], v[24:27]
	ds_read_b64_tr_b16 v[120:121], v104 offset:26272
	ds_read_b64_tr_b16 v[118:119], v104 offset:17568
	ds_read_b64_tr_b16 v[122:123], v104 offset:17600
	s_waitcnt lgkmcnt(5)
	v_mfma_f32_16x16x32_bf16 v[28:31], v[90:93], v[8:11], v[28:31]
	ds_read_b64_tr_b16 v[90:91], v104 offset:17632
	ds_read_b64_tr_b16 v[124:125], v104 offset:26304
	ds_read_b64_tr_b16 v[92:93], v104 offset:26336
	s_waitcnt lgkmcnt(6)
	v_mfma_f32_16x16x32_bf16 v[32:35], v[114:117], v[8:11], v[32:35]
	ds_read_b64_tr_b16 v[114:115], v104 offset:17664
	ds_read_b64_tr_b16 v[116:117], v104 offset:26368
	s_waitcnt lgkmcnt(6)
	v_mfma_f32_16x16x32_bf16 v[36:39], v[118:121], v[8:11], v[36:39]
	s_waitcnt lgkmcnt(3)
	v_mfma_f32_16x16x32_bf16 v[40:43], v[122:125], v[8:11], v[40:43]
	ds_read_b64_tr_b16 v[120:121], v104 offset:26400
	ds_read_b64_tr_b16 v[118:119], v104 offset:17696
	ds_read_b64_tr_b16 v[122:123], v104 offset:17728
	s_waitcnt lgkmcnt(5)
	v_mfma_f32_16x16x32_bf16 v[44:47], v[90:93], v[8:11], v[44:47]
	ds_read_b64_tr_b16 v[90:91], v104 offset:17760
	ds_read_b64_tr_b16 v[124:125], v104 offset:26432
	ds_read_b64_tr_b16 v[92:93], v104 offset:26464
	s_waitcnt lgkmcnt(6)
	v_mfma_f32_16x16x32_bf16 v[48:51], v[114:117], v[8:11], v[48:51]
	ds_read_b64_tr_b16 v[114:115], v104 offset:17792
	ds_read_b64_tr_b16 v[116:117], v104 offset:26496
	s_waitcnt lgkmcnt(6)
	v_mfma_f32_16x16x32_bf16 v[52:55], v[118:121], v[8:11], v[52:55]
	s_waitcnt lgkmcnt(3)
	v_mfma_f32_16x16x32_bf16 v[56:59], v[122:125], v[8:11], v[56:59]
	ds_read_b64_tr_b16 v[120:121], v104 offset:26528
	ds_read_b64_tr_b16 v[118:119], v104 offset:17824
	ds_read_b64_tr_b16 v[122:123], v104 offset:17856
	s_waitcnt lgkmcnt(5)
	v_mfma_f32_16x16x32_bf16 v[60:63], v[90:93], v[8:11], v[60:63]
	ds_read_b64_tr_b16 v[90:91], v104 offset:17888
	ds_read_b64_tr_b16 v[124:125], v104 offset:26560
	ds_read_b64_tr_b16 v[92:93], v104 offset:26592
	s_waitcnt lgkmcnt(6)
	v_mfma_f32_16x16x32_bf16 v[64:67], v[114:117], v[8:11], v[64:67]
	ds_read_b64_tr_b16 v[114:115], v104 offset:34816
	ds_read_b64_tr_b16 v[116:117], v104 offset:43520
	s_waitcnt lgkmcnt(6)
	v_mfma_f32_16x16x32_bf16 v[68:71], v[118:121], v[8:11], v[68:71]
	s_waitcnt lgkmcnt(3)
	v_mfma_f32_16x16x32_bf16 v[72:75], v[122:125], v[8:11], v[72:75]
	ds_read_b64_tr_b16 v[120:121], v104 offset:43552
	ds_read_b64_tr_b16 v[118:119], v104 offset:34848
	ds_read_b64_tr_b16 v[122:123], v104 offset:34880
	s_waitcnt lgkmcnt(5)
	v_mfma_f32_16x16x32_bf16 v[8:11], v[90:93], v[8:11], v[12:15]
	s_nop 2
	ds_read_b64_tr_b16 v[12:13], v104 offset:34912
	ds_read_b64_tr_b16 v[124:125], v104 offset:43584
	ds_read_b64_tr_b16 v[14:15], v104 offset:43616
	s_waitcnt lgkmcnt(6)
	v_mfma_f32_16x16x32_bf16 v[16:19], v[114:117], v[4:7], v[16:19]
	s_waitcnt lgkmcnt(4)
	v_mfma_f32_16x16x32_bf16 v[90:93], v[118:121], v[4:7], v[20:23]
	s_nop 2
	ds_read_b64_tr_b16 v[20:21], v104 offset:34944
	ds_read_b64_tr_b16 v[22:23], v104 offset:43648
	ds_read_b64_tr_b16 v[116:117], v104 offset:43680
	ds_read_b64_tr_b16 v[114:115], v104 offset:34976
	ds_read_b64_tr_b16 v[118:119], v104 offset:35008
	s_waitcnt lgkmcnt(5)
	v_mfma_f32_16x16x32_bf16 v[28:31], v[12:15], v[4:7], v[28:31]
	ds_read_b64_tr_b16 v[12:13], v104 offset:35040
	ds_read_b64_tr_b16 v[120:121], v104 offset:43712
	ds_read_b64_tr_b16 v[14:15], v104 offset:43744
	s_waitcnt lgkmcnt(6)
	v_mfma_f32_16x16x32_bf16 v[32:35], v[20:23], v[4:7], v[32:35]
	ds_read_b64_tr_b16 v[20:21], v104 offset:35072
	ds_read_b64_tr_b16 v[22:23], v104 offset:43776
	s_waitcnt lgkmcnt(6)
	v_mfma_f32_16x16x32_bf16 v[36:39], v[114:117], v[4:7], v[36:39]
	s_waitcnt lgkmcnt(3)
	v_mfma_f32_16x16x32_bf16 v[40:43], v[118:121], v[4:7], v[40:43]
	ds_read_b64_tr_b16 v[116:117], v104 offset:43808
	ds_read_b64_tr_b16 v[114:115], v104 offset:35104
	ds_read_b64_tr_b16 v[118:119], v104 offset:35136
	s_waitcnt lgkmcnt(5)
	v_mfma_f32_16x16x32_bf16 v[44:47], v[12:15], v[4:7], v[44:47]
	ds_read_b64_tr_b16 v[12:13], v104 offset:35168
	ds_read_b64_tr_b16 v[120:121], v104 offset:43840
	ds_read_b64_tr_b16 v[14:15], v104 offset:43872
	s_waitcnt lgkmcnt(6)
	v_mfma_f32_16x16x32_bf16 v[48:51], v[20:23], v[4:7], v[48:51]
	ds_read_b64_tr_b16 v[20:21], v104 offset:35200
	ds_read_b64_tr_b16 v[22:23], v104 offset:43904
	s_waitcnt lgkmcnt(6)
	v_mfma_f32_16x16x32_bf16 v[114:117], v[114:117], v[4:7], v[52:55]
	s_waitcnt lgkmcnt(3)
	v_mfma_f32_16x16x32_bf16 v[118:121], v[118:121], v[4:7], v[56:59]
	s_nop 0
	ds_read_b64_tr_b16 v[54:55], v104 offset:43936
	ds_read_b64_tr_b16 v[52:53], v104 offset:35232
	ds_read_b64_tr_b16 v[56:57], v104 offset:35264
	v_mfma_f32_16x16x32_bf16 v[24:27], v[122:125], v[4:7], v[24:27]
	s_waitcnt lgkmcnt(5)
	v_mfma_f32_16x16x32_bf16 v[122:125], v[12:15], v[4:7], v[60:63]
	ds_read_b64_tr_b16 v[12:13], v104 offset:35296
	ds_read_b64_tr_b16 v[58:59], v104 offset:43968
	ds_read_b64_tr_b16 v[14:15], v104 offset:44000
	ds_read_b64_tr_b16 v[60:61], v104 offset:52224
	ds_read_b64_tr_b16 v[62:63], v104 offset:60928
	s_waitcnt lgkmcnt(8)
	v_mfma_f32_16x16x32_bf16 v[126:129], v[20:23], v[4:7], v[64:67]
	s_waitcnt lgkmcnt(6)
	v_mfma_f32_16x16x32_bf16 v[130:133], v[52:55], v[4:7], v[68:71]
	ds_read_b64_tr_b16 v[54:55], v104 offset:60960
	ds_read_b64_tr_b16 v[52:53], v104 offset:52256
	ds_read_b64_tr_b16 v[64:65], v104 offset:52288
	s_waitcnt lgkmcnt(6)
	v_mfma_f32_16x16x32_bf16 v[20:23], v[56:59], v[4:7], v[72:75]
	ds_read_b64_tr_b16 v[56:57], v104 offset:52320
	ds_read_b64_tr_b16 v[66:67], v104 offset:60992
	ds_read_b64_tr_b16 v[58:59], v104 offset:61024
	s_waitcnt lgkmcnt(6)
	v_mfma_f32_16x16x32_bf16 v[134:137], v[60:63], v[0:3], v[16:19]
	s_nop 2
	ds_read_b64_tr_b16 v[16:17], v104 offset:52352
	ds_read_b64_tr_b16 v[18:19], v104 offset:61056
	v_add_u32_e32 v60, s6, v84
	v_ashrrev_i32_e32 v61, 31, v60
	s_waitcnt lgkmcnt(6)
	v_mfma_f32_16x16x32_bf16 v[138:141], v[52:55], v[0:3], v[90:93]
	s_waitcnt lgkmcnt(3)
	v_mfma_f32_16x16x32_bf16 v[72:75], v[64:67], v[0:3], v[24:27]
	s_nop 2
	ds_read_b64_tr_b16 v[26:27], v104 offset:61088
	ds_read_b64_tr_b16 v[24:25], v104 offset:52384
	ds_read_b64_tr_b16 v[52:53], v104 offset:52416
	v_lshlrev_b64 v[92:93], 11, v[60:61]
	v_add_u32_e32 v90, s0, v84
	s_waitcnt lgkmcnt(5)
	v_mfma_f32_16x16x32_bf16 v[68:71], v[56:59], v[0:3], v[28:31]
	s_nop 2
	ds_read_b64_tr_b16 v[28:29], v104 offset:52448
	ds_read_b64_tr_b16 v[54:55], v104 offset:61120
	ds_read_b64_tr_b16 v[30:31], v104 offset:61152
	v_ashrrev_i32_e32 v91, 31, v90
	v_lshl_add_u64 v[142:143], v[90:91], 2, s[42:43]
	s_waitcnt lgkmcnt(6)
	v_mfma_f32_16x16x32_bf16 v[64:67], v[16:19], v[0:3], v[32:35]
	ds_read_b64_tr_b16 v[16:17], v104 offset:52480
	ds_read_b64_tr_b16 v[18:19], v104 offset:61184
	s_waitcnt lgkmcnt(6)
	v_mfma_f32_16x16x32_bf16 v[60:63], v[24:27], v[0:3], v[36:39]
	ds_read_b64_tr_b16 v[26:27], v104 offset:61216
	ds_read_b64_tr_b16 v[24:25], v104 offset:52512
	ds_read_b64_tr_b16 v[32:33], v104 offset:52544
	s_waitcnt lgkmcnt(6)
	v_mfma_f32_16x16x32_bf16 v[56:59], v[52:55], v[0:3], v[40:43]
	s_waitcnt lgkmcnt(5)
	v_mfma_f32_16x16x32_bf16 v[52:55], v[28:31], v[0:3], v[44:47]
	ds_read_b64_tr_b16 v[28:29], v104 offset:52576
	ds_read_b64_tr_b16 v[34:35], v104 offset:61248
	ds_read_b64_tr_b16 v[30:31], v104 offset:61280
	s_waitcnt lgkmcnt(6)
	v_mfma_f32_16x16x32_bf16 v[48:51], v[16:19], v[0:3], v[48:51]
	v_lshl_add_u64 v[16:17], s[46:47], 0, v[92:93]
	v_lshl_add_u64 v[16:17], v[16:17], 0, s[8:9]
	v_lshl_add_u64 v[90:91], v[16:17], 0, v[76:77]
	s_waitcnt lgkmcnt(4)
	v_mfma_f32_16x16x32_bf16 v[44:47], v[24:27], v[0:3], v[114:117]
	ds_read_b64_tr_b16 v[94:95], v104 offset:61312
	ds_read_b64_tr_b16 v[92:93], v104 offset:52608
	s_nop 0
	ds_read_b64_tr_b16 v[114:115], v104 offset:52640
	ds_read_b64_tr_b16 v[24:25], v104 offset:52672
	ds_read_b64_tr_b16 v[16:17], v104 offset:52704
	s_waitcnt lgkmcnt(6)
	v_mfma_f32_16x16x32_bf16 v[40:43], v[32:35], v[0:3], v[118:121]
	s_nop 2
	s_waitcnt vmcnt(0)
	v_mov_b64_e32 v[118:119], v[144:145]
	ds_read_b64_tr_b16 v[116:117], v104 offset:61344
	ds_read_b64_tr_b16 v[26:27], v104 offset:61376
	ds_read_b64_tr_b16 v[18:19], v104 offset:61408
	s_waitcnt lgkmcnt(6)
	v_mfma_f32_16x16x32_bf16 v[32:35], v[92:95], v[0:3], v[126:129]
	v_lshlrev_b32_e32 v92, 16, v118
	v_and_b32_e32 v93, 0xffff0000, v118
	v_lshlrev_b32_e32 v94, 16, v119
	v_and_b32_e32 v95, 0xffff0000, v119
	v_mfma_f32_16x16x32_bf16 v[36:39], v[28:31], v[0:3], v[122:125]
	v_and_b32_e32 v127, 0x7fffffff, v95
	v_and_b32_e32 v126, 0x7fffffff, v94
	v_pk_fma_f32 v[126:127], v[126:127], s[12:13], 1.0 op_sel_hi:[1,0,0]
	v_and_b32_e32 v123, 0x7fffffff, v93
	v_and_b32_e32 v122, 0x7fffffff, v92
	v_pk_fma_f32 v[122:123], v[122:123], s[12:13], 1.0 op_sel_hi:[1,0,0]
	v_rcp_f32_e32 v126, v126
	v_rcp_f32_e32 v122, v122
	v_rcp_f32_e32 v123, v123
	v_rcp_f32_e32 v127, v127
	v_pk_mul_f32 v[124:125], v[92:93], v[92:93]
	v_pk_mul_f32 v[128:129], v[94:95], v[94:95]
	s_waitcnt lgkmcnt(2)
	v_mfma_f32_16x16x32_bf16 v[28:31], v[114:117], v[0:3], v[130:133]
	v_mul_f32_e64 v124, v124, s62
	v_mul_f32_e64 v125, v125, s62
	v_pk_mul_f32 v[128:129], v[128:129], s[62:63] op_sel_hi:[1,0]
	v_exp_f32_e32 v124, v124
	v_pk_fma_f32 v[130:131], v[122:123], s[36:37], v[88:89] op_sel_hi:[1,0,0]
	v_pk_fma_f32 v[132:133], v[126:127], s[36:37], v[88:89] op_sel_hi:[1,0,0]
	v_exp_f32_e32 v125, v125
	v_exp_f32_e32 v128, v128
	v_exp_f32_e32 v129, v129
	v_pk_fma_f32 v[130:131], v[122:123], v[130:131], s[38:39] op_sel_hi:[1,1,0]
	v_pk_fma_f32 v[132:133], v[126:127], v[132:133], s[38:39] op_sel_hi:[1,1,0]
	v_pk_fma_f32 v[130:131], v[122:123], v[130:131], s[40:41] op_sel_hi:[1,1,0]
	v_pk_fma_f32 v[132:133], v[126:127], v[132:133], s[40:41] op_sel_hi:[1,1,0]
	v_pk_fma_f32 v[130:131], v[122:123], v[130:131], s[60:61] op_sel_hi:[1,1,0]
	v_pk_fma_f32 v[132:133], v[126:127], v[132:133], s[60:61] op_sel_hi:[1,1,0]
	v_pk_mul_f32 v[122:123], v[122:123], v[130:131]
	v_pk_mul_f32 v[126:127], v[126:127], v[132:133]
	v_pk_mul_f32 v[122:123], v[124:125], v[122:123]
	v_pk_mul_f32 v[124:125], v[128:129], v[126:127]
	v_pk_mul_f32 v[126:127], v[92:93], v[122:123]
	v_pk_fma_f32 v[122:123], v[92:93], v[122:123], v[92:93] neg_lo:[1,0,0] neg_hi:[1,0,0]
	v_cmp_gt_f32_e32 vcc, 0, v93
	v_pk_mul_f32 v[128:129], v[94:95], v[124:125]
	v_pk_fma_f32 v[124:125], v[94:95], v[124:125], v[94:95] neg_lo:[1,0,0] neg_hi:[1,0,0]
	v_cmp_gt_f32_e64 s[0:1], 0, v94
	v_cmp_gt_f32_e64 s[4:5], 0, v95
	v_cmp_gt_f32_e64 s[6:7], 0, v92
	v_add_f32_e32 v114, v134, v113
	v_add_f32_e32 v115, v135, v113
	v_add_f32_e32 v116, v136, v113
	v_add_f32_e32 v117, v137, v113
	v_cndmask_b32_e64 v92, v122, v126, s[6:7]
	v_cndmask_b32_e32 v93, v123, v127, vcc
	v_cndmask_b32_e64 v94, v124, v128, s[0:1]
	v_cndmask_b32_e64 v95, v125, v129, s[4:5]
	v_mul_f32_e32 v92, v114, v92
	v_mul_f32_e32 v93, v115, v93
	v_mul_f32_e32 v94, v116, v94
	v_mul_f32_e32 v95, v117, v95
	v_cvt_pk_bf16_f32 v92, v92, v93
	v_cvt_pk_bf16_f32 v93, v94, v95
	v_mov_b64_e32 v[94:95], v[146:147]
	v_add_f32_e32 v118, v138, v113
	global_store_dwordx2 v[90:91], v[92:93], off
	v_add_f32_e32 v119, v139, v113
	v_add_f32_e32 v120, v140, v113
	v_add_f32_e32 v121, v141, v113
	v_add_f32_e32 v72, v72, v113
	v_add_f32_e32 v73, v73, v113
	v_add_f32_e32 v74, v74, v113
	v_add_f32_e32 v75, v75, v113
	v_add_f32_e32 v68, v68, v113
	v_add_f32_e32 v69, v69, v113
	v_add_f32_e32 v70, v70, v113
	v_add_f32_e32 v71, v71, v113
	v_add_f32_e32 v64, v64, v113
	v_add_f32_e32 v65, v65, v113
	v_add_f32_e32 v66, v66, v113
	v_add_f32_e32 v67, v67, v113
	v_add_f32_e32 v60, v60, v113
	v_add_f32_e32 v61, v61, v113
	v_add_f32_e32 v62, v62, v113
	v_add_f32_e32 v63, v63, v113
	v_add_f32_e32 v56, v56, v113
	v_add_f32_e32 v57, v57, v113
	v_add_f32_e32 v58, v58, v113
	v_add_f32_e32 v59, v59, v113
	v_add_f32_e32 v52, v52, v113
	v_add_f32_e32 v53, v53, v113
	v_add_f32_e32 v54, v54, v113
	v_add_f32_e32 v55, v55, v113
	v_add_f32_e32 v48, v48, v113
	v_add_f32_e32 v49, v49, v113
	v_add_f32_e32 v50, v50, v113
	v_add_f32_e32 v51, v51, v113
	v_add_f32_e32 v44, v44, v113
	v_add_f32_e32 v45, v45, v113
	v_add_f32_e32 v46, v46, v113
	v_add_f32_e32 v47, v47, v113
	v_add_f32_e32 v40, v40, v113
	v_add_f32_e32 v41, v41, v113
	v_add_f32_e32 v42, v42, v113
	v_add_f32_e32 v43, v43, v113
	v_add_f32_e32 v36, v36, v113
	v_add_f32_e32 v37, v37, v113
	v_add_f32_e32 v38, v38, v113
	v_add_f32_e32 v39, v39, v113
	v_add_f32_e32 v32, v32, v113
	v_add_f32_e32 v33, v33, v113
	v_add_f32_e32 v34, v34, v113
	v_add_f32_e32 v35, v35, v113
	v_add_f32_e32 v28, v28, v113
	v_add_f32_e32 v29, v29, v113
	v_add_f32_e32 v30, v30, v113
	v_add_f32_e32 v31, v31, v113
	s_waitcnt lgkmcnt(1)
	v_mfma_f32_16x16x32_bf16 v[20:23], v[24:27], v[0:3], v[20:23]
	v_lshlrev_b32_e32 v92, 16, v94
	v_and_b32_e32 v93, 0xffff0000, v94
	v_lshlrev_b32_e32 v94, 16, v95
	v_and_b32_e32 v95, 0xffff0000, v95
	v_and_b32_e32 v115, 0x7fffffff, v93
	v_and_b32_e32 v114, 0x7fffffff, v92
	v_and_b32_e32 v123, 0x7fffffff, v95
	v_and_b32_e32 v122, 0x7fffffff, v94
	v_pk_fma_f32 v[114:115], v[114:115], s[12:13], 1.0 op_sel_hi:[1,0,0]
	v_pk_fma_f32 v[122:123], v[122:123], s[12:13], 1.0 op_sel_hi:[1,0,0]
	v_rcp_f32_e32 v114, v114
	v_rcp_f32_e32 v115, v115
	v_rcp_f32_e32 v122, v122
	v_rcp_f32_e32 v123, v123
	v_pk_mul_f32 v[116:117], v[92:93], v[92:93]
	v_pk_mul_f32 v[124:125], v[94:95], v[94:95]
	v_pk_mul_f32 v[116:117], v[116:117], s[62:63] op_sel_hi:[1,0]
	v_pk_mul_f32 v[124:125], v[124:125], s[62:63] op_sel_hi:[1,0]
	v_pk_fma_f32 v[126:127], v[114:115], s[36:37], v[88:89] op_sel_hi:[1,0,0]
	v_pk_fma_f32 v[128:129], v[122:123], s[36:37], v[88:89] op_sel_hi:[1,0,0]
	v_exp_f32_e32 v116, v116
	v_exp_f32_e32 v117, v117
	v_exp_f32_e32 v124, v124
	v_exp_f32_e32 v125, v125
	v_pk_fma_f32 v[126:127], v[114:115], v[126:127], s[38:39] op_sel_hi:[1,1,0]
	v_pk_fma_f32 v[128:129], v[122:123], v[128:129], s[38:39] op_sel_hi:[1,1,0]
	v_pk_fma_f32 v[126:127], v[114:115], v[126:127], s[40:41] op_sel_hi:[1,1,0]
	v_pk_fma_f32 v[128:129], v[122:123], v[128:129], s[40:41] op_sel_hi:[1,1,0]
	v_pk_fma_f32 v[126:127], v[114:115], v[126:127], s[60:61] op_sel_hi:[1,1,0]
	v_pk_fma_f32 v[128:129], v[122:123], v[128:129], s[60:61] op_sel_hi:[1,1,0]
	v_pk_mul_f32 v[114:115], v[114:115], v[126:127]
	v_pk_mul_f32 v[122:123], v[122:123], v[128:129]
	v_pk_mul_f32 v[114:115], v[116:117], v[114:115]
	v_pk_mul_f32 v[116:117], v[124:125], v[122:123]
	v_pk_mul_f32 v[122:123], v[92:93], v[114:115]
	v_pk_fma_f32 v[114:115], v[92:93], v[114:115], v[92:93] neg_lo:[1,0,0] neg_hi:[1,0,0]
	v_cmp_gt_f32_e32 vcc, 0, v93
	v_pk_mul_f32 v[124:125], v[94:95], v[116:117]
	v_pk_fma_f32 v[116:117], v[94:95], v[116:117], v[94:95] neg_lo:[1,0,0] neg_hi:[1,0,0]
	v_cmp_gt_f32_e64 s[0:1], 0, v94
	v_cmp_gt_f32_e64 s[4:5], 0, v95
	v_cmp_gt_f32_e64 s[6:7], 0, v92
	v_cndmask_b32_e32 v93, v115, v123, vcc
	v_cndmask_b32_e64 v94, v116, v124, s[0:1]
	v_cndmask_b32_e64 v92, v114, v122, s[6:7]
	v_cndmask_b32_e64 v95, v117, v125, s[4:5]
	v_mul_f32_e32 v92, v118, v92
	v_mul_f32_e32 v93, v119, v93
	v_mul_f32_e32 v94, v120, v94
	v_mul_f32_e32 v95, v121, v95
	v_cvt_pk_bf16_f32 v92, v92, v93
	v_cvt_pk_bf16_f32 v93, v94, v95
	v_mov_b64_e32 v[94:95], v[148:149]
	v_mfma_f32_16x16x32_bf16 v[4:7], v[12:15], v[4:7], v[8:11]
	global_store_dwordx2 v[90:91], v[92:93], off offset:32
	v_lshlrev_b32_e32 v92, 16, v94
	v_and_b32_e32 v93, 0xffff0000, v94
	v_lshlrev_b32_e32 v94, 16, v95
	v_and_b32_e32 v95, 0xffff0000, v95
	v_and_b32_e32 v115, 0x7fffffff, v93
	v_and_b32_e32 v114, 0x7fffffff, v92
	v_and_b32_e32 v119, 0x7fffffff, v95
	v_and_b32_e32 v118, 0x7fffffff, v94
	v_pk_fma_f32 v[114:115], v[114:115], s[12:13], 1.0 op_sel_hi:[1,0,0]
	v_pk_fma_f32 v[118:119], v[118:119], s[12:13], 1.0 op_sel_hi:[1,0,0]
	v_rcp_f32_e32 v114, v114
	v_rcp_f32_e32 v115, v115
	v_rcp_f32_e32 v118, v118
	v_rcp_f32_e32 v119, v119
	v_pk_mul_f32 v[116:117], v[92:93], v[92:93]
	v_pk_mul_f32 v[120:121], v[94:95], v[94:95]
	v_pk_mul_f32 v[116:117], v[116:117], s[62:63] op_sel_hi:[1,0]
	v_pk_mul_f32 v[120:121], v[120:121], s[62:63] op_sel_hi:[1,0]
	v_pk_fma_f32 v[122:123], v[114:115], s[36:37], v[88:89] op_sel_hi:[1,0,0]
	v_pk_fma_f32 v[124:125], v[118:119], s[36:37], v[88:89] op_sel_hi:[1,0,0]
	v_exp_f32_e32 v116, v116
	v_exp_f32_e32 v117, v117
	v_exp_f32_e32 v120, v120
	v_exp_f32_e32 v121, v121
	v_pk_fma_f32 v[122:123], v[114:115], v[122:123], s[38:39] op_sel_hi:[1,1,0]
	v_pk_fma_f32 v[124:125], v[118:119], v[124:125], s[38:39] op_sel_hi:[1,1,0]
	v_pk_fma_f32 v[122:123], v[114:115], v[122:123], s[40:41] op_sel_hi:[1,1,0]
	v_pk_fma_f32 v[124:125], v[118:119], v[124:125], s[40:41] op_sel_hi:[1,1,0]
	v_pk_fma_f32 v[122:123], v[114:115], v[122:123], s[60:61] op_sel_hi:[1,1,0]
	v_pk_fma_f32 v[124:125], v[118:119], v[124:125], s[60:61] op_sel_hi:[1,1,0]
	v_pk_mul_f32 v[114:115], v[114:115], v[122:123]
	v_pk_mul_f32 v[118:119], v[118:119], v[124:125]
	v_pk_mul_f32 v[114:115], v[116:117], v[114:115]
	v_pk_mul_f32 v[116:117], v[120:121], v[118:119]
	v_pk_mul_f32 v[118:119], v[92:93], v[114:115]
	v_pk_fma_f32 v[114:115], v[92:93], v[114:115], v[92:93] neg_lo:[1,0,0] neg_hi:[1,0,0]
	v_cmp_gt_f32_e32 vcc, 0, v93
	v_pk_mul_f32 v[120:121], v[94:95], v[116:117]
	v_pk_fma_f32 v[116:117], v[94:95], v[116:117], v[94:95] neg_lo:[1,0,0] neg_hi:[1,0,0]
	v_cmp_gt_f32_e64 s[0:1], 0, v94
	v_cmp_gt_f32_e64 s[4:5], 0, v95
	v_cmp_gt_f32_e64 s[6:7], 0, v92
	v_cndmask_b32_e32 v93, v115, v119, vcc
	v_cndmask_b32_e64 v94, v116, v120, s[0:1]
	v_cndmask_b32_e64 v92, v114, v118, s[6:7]
	v_cndmask_b32_e64 v95, v117, v121, s[4:5]
	v_mul_f32_e32 v72, v72, v92
	v_mul_f32_e32 v73, v73, v93
	v_mul_f32_e32 v74, v74, v94
	v_mul_f32_e32 v75, v75, v95
	v_cvt_pk_bf16_f32 v72, v72, v73
	v_cvt_pk_bf16_f32 v73, v74, v75
	v_mov_b64_e32 v[74:75], v[150:151]
	s_waitcnt lgkmcnt(0)
	v_mfma_f32_16x16x32_bf16 v[0:3], v[16:19], v[0:3], v[4:7]
	global_store_dwordx2 v[90:91], v[72:73], off offset:64
	v_lshlrev_b32_e32 v72, 16, v74
	v_and_b32_e32 v73, 0xffff0000, v74
	v_lshlrev_b32_e32 v74, 16, v75
	v_and_b32_e32 v75, 0xffff0000, v75
	v_and_b32_e32 v93, 0x7fffffff, v73
	v_and_b32_e32 v92, 0x7fffffff, v72
	v_and_b32_e32 v115, 0x7fffffff, v75
	v_and_b32_e32 v114, 0x7fffffff, v74
	v_pk_fma_f32 v[92:93], v[92:93], s[12:13], 1.0 op_sel_hi:[1,0,0]
	v_pk_fma_f32 v[114:115], v[114:115], s[12:13], 1.0 op_sel_hi:[1,0,0]
	v_rcp_f32_e32 v92, v92
	v_rcp_f32_e32 v93, v93
	v_rcp_f32_e32 v114, v114
	v_rcp_f32_e32 v115, v115
	v_pk_mul_f32 v[94:95], v[72:73], v[72:73]
	v_pk_mul_f32 v[116:117], v[74:75], v[74:75]
	v_pk_mul_f32 v[94:95], v[94:95], s[62:63] op_sel_hi:[1,0]
	v_pk_mul_f32 v[116:117], v[116:117], s[62:63] op_sel_hi:[1,0]
	v_pk_fma_f32 v[118:119], v[92:93], s[36:37], v[88:89] op_sel_hi:[1,0,0]
	v_pk_fma_f32 v[120:121], v[114:115], s[36:37], v[88:89] op_sel_hi:[1,0,0]
	v_exp_f32_e32 v94, v94
	v_exp_f32_e32 v95, v95
	v_exp_f32_e32 v116, v116
	v_exp_f32_e32 v117, v117
	v_pk_fma_f32 v[118:119], v[92:93], v[118:119], s[38:39] op_sel_hi:[1,1,0]
	v_pk_fma_f32 v[120:121], v[114:115], v[120:121], s[38:39] op_sel_hi:[1,1,0]
	v_pk_fma_f32 v[118:119], v[92:93], v[118:119], s[40:41] op_sel_hi:[1,1,0]
	v_pk_fma_f32 v[120:121], v[114:115], v[120:121], s[40:41] op_sel_hi:[1,1,0]
	v_pk_fma_f32 v[118:119], v[92:93], v[118:119], s[60:61] op_sel_hi:[1,1,0]
	v_pk_fma_f32 v[120:121], v[114:115], v[120:121], s[60:61] op_sel_hi:[1,1,0]
	v_pk_mul_f32 v[92:93], v[92:93], v[118:119]
	v_pk_mul_f32 v[114:115], v[114:115], v[120:121]
	v_pk_mul_f32 v[92:93], v[94:95], v[92:93]
	v_pk_mul_f32 v[94:95], v[116:117], v[114:115]
	v_pk_mul_f32 v[114:115], v[72:73], v[92:93]
	v_pk_fma_f32 v[92:93], v[72:73], v[92:93], v[72:73] neg_lo:[1,0,0] neg_hi:[1,0,0]
	v_cmp_gt_f32_e32 vcc, 0, v73
	v_pk_mul_f32 v[116:117], v[74:75], v[94:95]
	v_pk_fma_f32 v[94:95], v[74:75], v[94:95], v[74:75] neg_lo:[1,0,0] neg_hi:[1,0,0]
	v_cmp_gt_f32_e64 s[0:1], 0, v74
	v_cmp_gt_f32_e64 s[4:5], 0, v75
	v_cmp_gt_f32_e64 s[6:7], 0, v72
	v_cndmask_b32_e32 v73, v93, v115, vcc
	v_cndmask_b32_e64 v74, v94, v116, s[0:1]
	v_cndmask_b32_e64 v72, v92, v114, s[6:7]
	v_cndmask_b32_e64 v75, v95, v117, s[4:5]
	v_mul_f32_e32 v68, v68, v72
	v_mul_f32_e32 v69, v69, v73
	v_mul_f32_e32 v70, v70, v74
	v_mul_f32_e32 v71, v71, v75
	v_cvt_pk_bf16_f32 v68, v68, v69
	v_cvt_pk_bf16_f32 v69, v70, v71
	v_mov_b64_e32 v[70:71], v[152:153]
	v_add_f32_e32 v16, v113, v0
	global_store_dwordx2 v[90:91], v[68:69], off offset:96
	v_add_f32_e32 v17, v113, v1
	v_add_f32_e32 v18, v113, v2
	v_add_f32_e32 v19, v113, v3
	v_lshlrev_b32_e32 v68, 16, v70
	v_and_b32_e32 v69, 0xffff0000, v70
	v_lshlrev_b32_e32 v70, 16, v71
	v_and_b32_e32 v71, 0xffff0000, v71
	v_and_b32_e32 v73, 0x7fffffff, v69
	v_and_b32_e32 v72, 0x7fffffff, v68
	v_and_b32_e32 v93, 0x7fffffff, v71
	v_and_b32_e32 v92, 0x7fffffff, v70
	v_pk_fma_f32 v[72:73], v[72:73], s[12:13], 1.0 op_sel_hi:[1,0,0]
	v_pk_fma_f32 v[92:93], v[92:93], s[12:13], 1.0 op_sel_hi:[1,0,0]
	v_rcp_f32_e32 v72, v72
	v_rcp_f32_e32 v73, v73
	v_rcp_f32_e32 v92, v92
	v_rcp_f32_e32 v93, v93
	v_pk_mul_f32 v[74:75], v[68:69], v[68:69]
	v_pk_mul_f32 v[94:95], v[70:71], v[70:71]
	v_pk_mul_f32 v[74:75], v[74:75], s[62:63] op_sel_hi:[1,0]
	v_pk_mul_f32 v[94:95], v[94:95], s[62:63] op_sel_hi:[1,0]
	v_pk_fma_f32 v[114:115], v[72:73], s[36:37], v[88:89] op_sel_hi:[1,0,0]
	v_pk_fma_f32 v[116:117], v[92:93], s[36:37], v[88:89] op_sel_hi:[1,0,0]
	v_exp_f32_e32 v74, v74
	v_exp_f32_e32 v75, v75
	v_exp_f32_e32 v94, v94
	v_exp_f32_e32 v95, v95
	v_pk_fma_f32 v[114:115], v[72:73], v[114:115], s[38:39] op_sel_hi:[1,1,0]
	v_pk_fma_f32 v[116:117], v[92:93], v[116:117], s[38:39] op_sel_hi:[1,1,0]
	v_pk_fma_f32 v[114:115], v[72:73], v[114:115], s[40:41] op_sel_hi:[1,1,0]
	v_pk_fma_f32 v[116:117], v[92:93], v[116:117], s[40:41] op_sel_hi:[1,1,0]
	v_pk_fma_f32 v[114:115], v[72:73], v[114:115], s[60:61] op_sel_hi:[1,1,0]
	v_pk_fma_f32 v[116:117], v[92:93], v[116:117], s[60:61] op_sel_hi:[1,1,0]
	v_pk_mul_f32 v[72:73], v[72:73], v[114:115]
	v_pk_mul_f32 v[92:93], v[92:93], v[116:117]
	v_pk_mul_f32 v[72:73], v[74:75], v[72:73]
	v_pk_mul_f32 v[74:75], v[94:95], v[92:93]
	v_pk_mul_f32 v[92:93], v[68:69], v[72:73]
	v_pk_fma_f32 v[72:73], v[68:69], v[72:73], v[68:69] neg_lo:[1,0,0] neg_hi:[1,0,0]
	v_cmp_gt_f32_e32 vcc, 0, v69
	v_pk_mul_f32 v[94:95], v[70:71], v[74:75]
	v_pk_fma_f32 v[74:75], v[70:71], v[74:75], v[70:71] neg_lo:[1,0,0] neg_hi:[1,0,0]
	v_cmp_gt_f32_e64 s[0:1], 0, v70
	v_cmp_gt_f32_e64 s[4:5], 0, v71
	v_cmp_gt_f32_e64 s[6:7], 0, v68
	v_cndmask_b32_e32 v69, v73, v93, vcc
	v_cndmask_b32_e64 v70, v74, v94, s[0:1]
	v_cndmask_b32_e64 v68, v72, v92, s[6:7]
	v_cndmask_b32_e64 v71, v75, v95, s[4:5]
	v_mul_f32_e32 v64, v64, v68
	v_mul_f32_e32 v65, v65, v69
	v_mul_f32_e32 v66, v66, v70
	v_mul_f32_e32 v67, v67, v71
	v_cvt_pk_bf16_f32 v64, v64, v65
	v_cvt_pk_bf16_f32 v65, v66, v67
	v_mov_b64_e32 v[66:67], v[154:155]
	s_nop 0
	global_store_dwordx2 v[90:91], v[64:65], off offset:128
	v_lshlrev_b32_e32 v64, 16, v66
	v_and_b32_e32 v65, 0xffff0000, v66
	v_lshlrev_b32_e32 v66, 16, v67
	v_and_b32_e32 v67, 0xffff0000, v67
	v_and_b32_e32 v69, 0x7fffffff, v65
	v_and_b32_e32 v68, 0x7fffffff, v64
	v_and_b32_e32 v73, 0x7fffffff, v67
	v_and_b32_e32 v72, 0x7fffffff, v66
	v_pk_fma_f32 v[68:69], v[68:69], s[12:13], 1.0 op_sel_hi:[1,0,0]
	v_pk_fma_f32 v[72:73], v[72:73], s[12:13], 1.0 op_sel_hi:[1,0,0]
	v_rcp_f32_e32 v68, v68
	v_rcp_f32_e32 v69, v69
	v_rcp_f32_e32 v72, v72
	v_rcp_f32_e32 v73, v73
	v_pk_mul_f32 v[70:71], v[64:65], v[64:65]
	v_pk_mul_f32 v[74:75], v[66:67], v[66:67]
	v_pk_mul_f32 v[70:71], v[70:71], s[62:63] op_sel_hi:[1,0]
	v_pk_mul_f32 v[74:75], v[74:75], s[62:63] op_sel_hi:[1,0]
	v_pk_fma_f32 v[92:93], v[68:69], s[36:37], v[88:89] op_sel_hi:[1,0,0]
	v_pk_fma_f32 v[94:95], v[72:73], s[36:37], v[88:89] op_sel_hi:[1,0,0]
	v_exp_f32_e32 v70, v70
	v_exp_f32_e32 v71, v71
	v_exp_f32_e32 v74, v74
	v_exp_f32_e32 v75, v75
	v_pk_fma_f32 v[92:93], v[68:69], v[92:93], s[38:39] op_sel_hi:[1,1,0]
	v_pk_fma_f32 v[94:95], v[72:73], v[94:95], s[38:39] op_sel_hi:[1,1,0]
	v_pk_fma_f32 v[92:93], v[68:69], v[92:93], s[40:41] op_sel_hi:[1,1,0]
	v_pk_fma_f32 v[94:95], v[72:73], v[94:95], s[40:41] op_sel_hi:[1,1,0]
	v_pk_fma_f32 v[92:93], v[68:69], v[92:93], s[60:61] op_sel_hi:[1,1,0]
	v_pk_fma_f32 v[94:95], v[72:73], v[94:95], s[60:61] op_sel_hi:[1,1,0]
	v_pk_mul_f32 v[68:69], v[68:69], v[92:93]
	v_pk_mul_f32 v[72:73], v[72:73], v[94:95]
	v_pk_mul_f32 v[68:69], v[70:71], v[68:69]
	v_pk_mul_f32 v[70:71], v[74:75], v[72:73]
	v_pk_mul_f32 v[72:73], v[64:65], v[68:69]
	v_pk_fma_f32 v[68:69], v[64:65], v[68:69], v[64:65] neg_lo:[1,0,0] neg_hi:[1,0,0]
	v_cmp_gt_f32_e32 vcc, 0, v65
	v_pk_mul_f32 v[74:75], v[66:67], v[70:71]
	v_pk_fma_f32 v[70:71], v[66:67], v[70:71], v[66:67] neg_lo:[1,0,0] neg_hi:[1,0,0]
	v_cmp_gt_f32_e64 s[0:1], 0, v66
	v_cmp_gt_f32_e64 s[4:5], 0, v67
	v_cmp_gt_f32_e64 s[6:7], 0, v64
	v_cndmask_b32_e32 v65, v69, v73, vcc
	v_cndmask_b32_e64 v66, v70, v74, s[0:1]
	v_cndmask_b32_e64 v64, v68, v72, s[6:7]
	v_cndmask_b32_e64 v67, v71, v75, s[4:5]
	v_mul_f32_e32 v60, v60, v64
	v_mul_f32_e32 v61, v61, v65
	v_mul_f32_e32 v62, v62, v66
	v_mul_f32_e32 v63, v63, v67
	v_cvt_pk_bf16_f32 v60, v60, v61
	v_cvt_pk_bf16_f32 v61, v62, v63
	v_mov_b64_e32 v[62:63], v[156:157]
	s_nop 0
	global_store_dwordx2 v[90:91], v[60:61], off offset:160
	v_lshlrev_b32_e32 v60, 16, v62
	v_and_b32_e32 v61, 0xffff0000, v62
	v_lshlrev_b32_e32 v62, 16, v63
	v_and_b32_e32 v63, 0xffff0000, v63
	v_and_b32_e32 v65, 0x7fffffff, v61
	v_and_b32_e32 v64, 0x7fffffff, v60
	v_and_b32_e32 v69, 0x7fffffff, v63
	v_and_b32_e32 v68, 0x7fffffff, v62
	v_pk_fma_f32 v[64:65], v[64:65], s[12:13], 1.0 op_sel_hi:[1,0,0]
	v_pk_fma_f32 v[68:69], v[68:69], s[12:13], 1.0 op_sel_hi:[1,0,0]
	v_rcp_f32_e32 v64, v64
	v_rcp_f32_e32 v65, v65
	v_rcp_f32_e32 v68, v68
	v_rcp_f32_e32 v69, v69
	v_pk_mul_f32 v[66:67], v[60:61], v[60:61]
	v_pk_mul_f32 v[70:71], v[62:63], v[62:63]
	v_pk_mul_f32 v[66:67], v[66:67], s[62:63] op_sel_hi:[1,0]
	v_pk_mul_f32 v[70:71], v[70:71], s[62:63] op_sel_hi:[1,0]
	v_pk_fma_f32 v[72:73], v[64:65], s[36:37], v[88:89] op_sel_hi:[1,0,0]
	v_pk_fma_f32 v[74:75], v[68:69], s[36:37], v[88:89] op_sel_hi:[1,0,0]
	v_exp_f32_e32 v66, v66
	v_exp_f32_e32 v67, v67
	v_exp_f32_e32 v70, v70
	v_exp_f32_e32 v71, v71
	v_pk_fma_f32 v[72:73], v[64:65], v[72:73], s[38:39] op_sel_hi:[1,1,0]
	v_pk_fma_f32 v[74:75], v[68:69], v[74:75], s[38:39] op_sel_hi:[1,1,0]
	v_pk_fma_f32 v[72:73], v[64:65], v[72:73], s[40:41] op_sel_hi:[1,1,0]
	v_pk_fma_f32 v[74:75], v[68:69], v[74:75], s[40:41] op_sel_hi:[1,1,0]
	v_pk_fma_f32 v[72:73], v[64:65], v[72:73], s[60:61] op_sel_hi:[1,1,0]
	v_pk_fma_f32 v[74:75], v[68:69], v[74:75], s[60:61] op_sel_hi:[1,1,0]
	v_pk_mul_f32 v[64:65], v[64:65], v[72:73]
	v_pk_mul_f32 v[68:69], v[68:69], v[74:75]
	v_pk_mul_f32 v[64:65], v[66:67], v[64:65]
	v_pk_mul_f32 v[66:67], v[70:71], v[68:69]
	v_pk_mul_f32 v[68:69], v[60:61], v[64:65]
	v_pk_fma_f32 v[64:65], v[60:61], v[64:65], v[60:61] neg_lo:[1,0,0] neg_hi:[1,0,0]
	v_cmp_gt_f32_e32 vcc, 0, v61
	v_pk_mul_f32 v[70:71], v[62:63], v[66:67]
	v_pk_fma_f32 v[66:67], v[62:63], v[66:67], v[62:63] neg_lo:[1,0,0] neg_hi:[1,0,0]
	v_cmp_gt_f32_e64 s[0:1], 0, v62
	v_cmp_gt_f32_e64 s[4:5], 0, v63
	v_cmp_gt_f32_e64 s[6:7], 0, v60
	v_cndmask_b32_e32 v61, v65, v69, vcc
	v_cndmask_b32_e64 v62, v66, v70, s[0:1]
	v_cndmask_b32_e64 v60, v64, v68, s[6:7]
	v_cndmask_b32_e64 v63, v67, v71, s[4:5]
	v_mul_f32_e32 v56, v56, v60
	v_mul_f32_e32 v57, v57, v61
	v_mul_f32_e32 v58, v58, v62
	v_mul_f32_e32 v59, v59, v63
	v_cvt_pk_bf16_f32 v56, v56, v57
	v_cvt_pk_bf16_f32 v57, v58, v59
	v_mov_b64_e32 v[58:59], v[158:159]
	s_nop 0
	global_store_dwordx2 v[90:91], v[56:57], off offset:192
	v_lshlrev_b32_e32 v56, 16, v58
	v_and_b32_e32 v57, 0xffff0000, v58
	v_lshlrev_b32_e32 v58, 16, v59
	v_and_b32_e32 v59, 0xffff0000, v59
	v_and_b32_e32 v61, 0x7fffffff, v57
	v_and_b32_e32 v60, 0x7fffffff, v56
	v_and_b32_e32 v65, 0x7fffffff, v59
	v_and_b32_e32 v64, 0x7fffffff, v58
	v_pk_fma_f32 v[60:61], v[60:61], s[12:13], 1.0 op_sel_hi:[1,0,0]
	v_pk_fma_f32 v[64:65], v[64:65], s[12:13], 1.0 op_sel_hi:[1,0,0]
	v_rcp_f32_e32 v60, v60
	v_rcp_f32_e32 v61, v61
	v_rcp_f32_e32 v64, v64
	v_rcp_f32_e32 v65, v65
	v_pk_mul_f32 v[62:63], v[56:57], v[56:57]
	v_pk_mul_f32 v[66:67], v[58:59], v[58:59]
	v_pk_mul_f32 v[62:63], v[62:63], s[62:63] op_sel_hi:[1,0]
	v_pk_mul_f32 v[66:67], v[66:67], s[62:63] op_sel_hi:[1,0]
	v_pk_fma_f32 v[68:69], v[60:61], s[36:37], v[88:89] op_sel_hi:[1,0,0]
	v_pk_fma_f32 v[70:71], v[64:65], s[36:37], v[88:89] op_sel_hi:[1,0,0]
	v_exp_f32_e32 v62, v62
	v_exp_f32_e32 v63, v63
	v_exp_f32_e32 v66, v66
	v_exp_f32_e32 v67, v67
	v_pk_fma_f32 v[68:69], v[60:61], v[68:69], s[38:39] op_sel_hi:[1,1,0]
	v_pk_fma_f32 v[70:71], v[64:65], v[70:71], s[38:39] op_sel_hi:[1,1,0]
	v_pk_fma_f32 v[68:69], v[60:61], v[68:69], s[40:41] op_sel_hi:[1,1,0]
	v_pk_fma_f32 v[70:71], v[64:65], v[70:71], s[40:41] op_sel_hi:[1,1,0]
	v_pk_fma_f32 v[68:69], v[60:61], v[68:69], s[60:61] op_sel_hi:[1,1,0]
	v_pk_fma_f32 v[70:71], v[64:65], v[70:71], s[60:61] op_sel_hi:[1,1,0]
	v_pk_mul_f32 v[60:61], v[60:61], v[68:69]
	v_pk_mul_f32 v[64:65], v[64:65], v[70:71]
	v_pk_mul_f32 v[60:61], v[62:63], v[60:61]
	v_pk_mul_f32 v[62:63], v[66:67], v[64:65]
	v_pk_mul_f32 v[64:65], v[56:57], v[60:61]
	v_pk_fma_f32 v[60:61], v[56:57], v[60:61], v[56:57] neg_lo:[1,0,0] neg_hi:[1,0,0]
	v_cmp_gt_f32_e32 vcc, 0, v57
	v_pk_mul_f32 v[66:67], v[58:59], v[62:63]
	v_pk_fma_f32 v[62:63], v[58:59], v[62:63], v[58:59] neg_lo:[1,0,0] neg_hi:[1,0,0]
	v_cmp_gt_f32_e64 s[0:1], 0, v58
	v_cmp_gt_f32_e64 s[4:5], 0, v59
	v_cmp_gt_f32_e64 s[6:7], 0, v56
	v_cndmask_b32_e32 v57, v61, v65, vcc
	v_cndmask_b32_e64 v58, v62, v66, s[0:1]
	v_cndmask_b32_e64 v56, v60, v64, s[6:7]
	v_cndmask_b32_e64 v59, v63, v67, s[4:5]
	v_mul_f32_e32 v52, v52, v56
	v_mul_f32_e32 v53, v53, v57
	v_mul_f32_e32 v54, v54, v58
	v_mul_f32_e32 v55, v55, v59
	v_cvt_pk_bf16_f32 v52, v52, v53
	v_cvt_pk_bf16_f32 v53, v54, v55
	v_mov_b64_e32 v[54:55], v[160:161]
	s_nop 0
	global_store_dwordx2 v[90:91], v[52:53], off offset:224
	v_lshlrev_b32_e32 v52, 16, v54
	v_and_b32_e32 v53, 0xffff0000, v54
	v_lshlrev_b32_e32 v54, 16, v55
	v_and_b32_e32 v55, 0xffff0000, v55
	v_and_b32_e32 v57, 0x7fffffff, v53
	v_and_b32_e32 v56, 0x7fffffff, v52
	v_and_b32_e32 v61, 0x7fffffff, v55
	v_and_b32_e32 v60, 0x7fffffff, v54
	v_pk_fma_f32 v[56:57], v[56:57], s[12:13], 1.0 op_sel_hi:[1,0,0]
	v_pk_fma_f32 v[60:61], v[60:61], s[12:13], 1.0 op_sel_hi:[1,0,0]
	v_rcp_f32_e32 v56, v56
	v_rcp_f32_e32 v57, v57
	v_rcp_f32_e32 v60, v60
	v_rcp_f32_e32 v61, v61
	v_pk_mul_f32 v[58:59], v[52:53], v[52:53]
	v_pk_mul_f32 v[62:63], v[54:55], v[54:55]
	v_pk_mul_f32 v[58:59], v[58:59], s[62:63] op_sel_hi:[1,0]
	v_pk_mul_f32 v[62:63], v[62:63], s[62:63] op_sel_hi:[1,0]
	v_pk_fma_f32 v[64:65], v[56:57], s[36:37], v[88:89] op_sel_hi:[1,0,0]
	v_pk_fma_f32 v[66:67], v[60:61], s[36:37], v[88:89] op_sel_hi:[1,0,0]
	v_exp_f32_e32 v58, v58
	v_exp_f32_e32 v59, v59
	v_exp_f32_e32 v62, v62
	v_exp_f32_e32 v63, v63
	v_pk_fma_f32 v[64:65], v[56:57], v[64:65], s[38:39] op_sel_hi:[1,1,0]
	v_pk_fma_f32 v[66:67], v[60:61], v[66:67], s[38:39] op_sel_hi:[1,1,0]
	v_pk_fma_f32 v[64:65], v[56:57], v[64:65], s[40:41] op_sel_hi:[1,1,0]
	v_pk_fma_f32 v[66:67], v[60:61], v[66:67], s[40:41] op_sel_hi:[1,1,0]
	v_pk_fma_f32 v[64:65], v[56:57], v[64:65], s[60:61] op_sel_hi:[1,1,0]
	v_pk_fma_f32 v[66:67], v[60:61], v[66:67], s[60:61] op_sel_hi:[1,1,0]
	v_pk_mul_f32 v[56:57], v[56:57], v[64:65]
	v_pk_mul_f32 v[60:61], v[60:61], v[66:67]
	v_pk_mul_f32 v[56:57], v[58:59], v[56:57]
	v_pk_mul_f32 v[58:59], v[62:63], v[60:61]
	v_pk_mul_f32 v[60:61], v[52:53], v[56:57]
	v_pk_fma_f32 v[56:57], v[52:53], v[56:57], v[52:53] neg_lo:[1,0,0] neg_hi:[1,0,0]
	v_cmp_gt_f32_e32 vcc, 0, v53
	v_pk_mul_f32 v[62:63], v[54:55], v[58:59]
	v_pk_fma_f32 v[58:59], v[54:55], v[58:59], v[54:55] neg_lo:[1,0,0] neg_hi:[1,0,0]
	v_cmp_gt_f32_e64 s[0:1], 0, v54
	v_cmp_gt_f32_e64 s[4:5], 0, v55
	v_cmp_gt_f32_e64 s[6:7], 0, v52
	v_cndmask_b32_e32 v53, v57, v61, vcc
	v_cndmask_b32_e64 v54, v58, v62, s[0:1]
	v_cndmask_b32_e64 v52, v56, v60, s[6:7]
	v_cndmask_b32_e64 v55, v59, v63, s[4:5]
	v_mul_f32_e32 v48, v48, v52
	v_mul_f32_e32 v49, v49, v53
	v_mul_f32_e32 v50, v50, v54
	v_mul_f32_e32 v51, v51, v55
	v_cvt_pk_bf16_f32 v48, v48, v49
	v_cvt_pk_bf16_f32 v49, v50, v51
	v_mov_b64_e32 v[50:51], v[162:163]
	s_nop 0
	global_store_dwordx2 v[90:91], v[48:49], off offset:256
	v_lshlrev_b32_e32 v48, 16, v50
	v_and_b32_e32 v49, 0xffff0000, v50
	v_lshlrev_b32_e32 v50, 16, v51
	v_and_b32_e32 v51, 0xffff0000, v51
	v_and_b32_e32 v53, 0x7fffffff, v49
	v_and_b32_e32 v52, 0x7fffffff, v48
	v_and_b32_e32 v57, 0x7fffffff, v51
	v_and_b32_e32 v56, 0x7fffffff, v50
	v_pk_fma_f32 v[52:53], v[52:53], s[12:13], 1.0 op_sel_hi:[1,0,0]
	v_pk_fma_f32 v[56:57], v[56:57], s[12:13], 1.0 op_sel_hi:[1,0,0]
	v_rcp_f32_e32 v52, v52
	v_rcp_f32_e32 v53, v53
	v_rcp_f32_e32 v56, v56
	v_rcp_f32_e32 v57, v57
	v_pk_mul_f32 v[54:55], v[48:49], v[48:49]
	v_pk_mul_f32 v[58:59], v[50:51], v[50:51]
	v_pk_mul_f32 v[54:55], v[54:55], s[62:63] op_sel_hi:[1,0]
	v_pk_mul_f32 v[58:59], v[58:59], s[62:63] op_sel_hi:[1,0]
	v_pk_fma_f32 v[60:61], v[52:53], s[36:37], v[88:89] op_sel_hi:[1,0,0]
	v_pk_fma_f32 v[62:63], v[56:57], s[36:37], v[88:89] op_sel_hi:[1,0,0]
	v_exp_f32_e32 v54, v54
	v_exp_f32_e32 v55, v55
	v_exp_f32_e32 v58, v58
	v_exp_f32_e32 v59, v59
	v_pk_fma_f32 v[60:61], v[52:53], v[60:61], s[38:39] op_sel_hi:[1,1,0]
	v_pk_fma_f32 v[62:63], v[56:57], v[62:63], s[38:39] op_sel_hi:[1,1,0]
	v_pk_fma_f32 v[60:61], v[52:53], v[60:61], s[40:41] op_sel_hi:[1,1,0]
	v_pk_fma_f32 v[62:63], v[56:57], v[62:63], s[40:41] op_sel_hi:[1,1,0]
	v_pk_fma_f32 v[60:61], v[52:53], v[60:61], s[60:61] op_sel_hi:[1,1,0]
	v_pk_fma_f32 v[62:63], v[56:57], v[62:63], s[60:61] op_sel_hi:[1,1,0]
	v_pk_mul_f32 v[52:53], v[52:53], v[60:61]
	v_pk_mul_f32 v[56:57], v[56:57], v[62:63]
	v_pk_mul_f32 v[52:53], v[54:55], v[52:53]
	v_pk_mul_f32 v[54:55], v[58:59], v[56:57]
	v_pk_mul_f32 v[56:57], v[48:49], v[52:53]
	v_pk_fma_f32 v[52:53], v[48:49], v[52:53], v[48:49] neg_lo:[1,0,0] neg_hi:[1,0,0]
	v_cmp_gt_f32_e32 vcc, 0, v49
	v_pk_mul_f32 v[58:59], v[50:51], v[54:55]
	v_pk_fma_f32 v[54:55], v[50:51], v[54:55], v[50:51] neg_lo:[1,0,0] neg_hi:[1,0,0]
	v_cmp_gt_f32_e64 s[0:1], 0, v50
	v_cmp_gt_f32_e64 s[4:5], 0, v51
	v_cmp_gt_f32_e64 s[6:7], 0, v48
	v_cndmask_b32_e32 v49, v53, v57, vcc
	v_cndmask_b32_e64 v50, v54, v58, s[0:1]
	v_cndmask_b32_e64 v48, v52, v56, s[6:7]
	v_cndmask_b32_e64 v51, v55, v59, s[4:5]
	v_mul_f32_e32 v44, v44, v48
	v_mul_f32_e32 v45, v45, v49
	v_mul_f32_e32 v46, v46, v50
	v_mul_f32_e32 v47, v47, v51
	v_cvt_pk_bf16_f32 v44, v44, v45
	v_cvt_pk_bf16_f32 v45, v46, v47
	v_mov_b64_e32 v[46:47], v[164:165]
	s_nop 0
	global_store_dwordx2 v[90:91], v[44:45], off offset:288
	v_lshlrev_b32_e32 v44, 16, v46
	v_and_b32_e32 v45, 0xffff0000, v46
	v_lshlrev_b32_e32 v46, 16, v47
	v_and_b32_e32 v47, 0xffff0000, v47
	v_and_b32_e32 v49, 0x7fffffff, v45
	v_and_b32_e32 v48, 0x7fffffff, v44
	v_and_b32_e32 v53, 0x7fffffff, v47
	v_and_b32_e32 v52, 0x7fffffff, v46
	v_pk_fma_f32 v[48:49], v[48:49], s[12:13], 1.0 op_sel_hi:[1,0,0]
	v_pk_fma_f32 v[52:53], v[52:53], s[12:13], 1.0 op_sel_hi:[1,0,0]
	v_rcp_f32_e32 v48, v48
	v_rcp_f32_e32 v49, v49
	v_rcp_f32_e32 v52, v52
	v_rcp_f32_e32 v53, v53
	v_pk_mul_f32 v[50:51], v[44:45], v[44:45]
	v_pk_mul_f32 v[54:55], v[46:47], v[46:47]
	v_pk_mul_f32 v[50:51], v[50:51], s[62:63] op_sel_hi:[1,0]
	v_pk_mul_f32 v[54:55], v[54:55], s[62:63] op_sel_hi:[1,0]
	v_pk_fma_f32 v[56:57], v[48:49], s[36:37], v[88:89] op_sel_hi:[1,0,0]
	v_pk_fma_f32 v[58:59], v[52:53], s[36:37], v[88:89] op_sel_hi:[1,0,0]
	v_exp_f32_e32 v50, v50
	v_exp_f32_e32 v51, v51
	v_exp_f32_e32 v54, v54
	v_exp_f32_e32 v55, v55
	v_pk_fma_f32 v[56:57], v[48:49], v[56:57], s[38:39] op_sel_hi:[1,1,0]
	v_pk_fma_f32 v[58:59], v[52:53], v[58:59], s[38:39] op_sel_hi:[1,1,0]
	v_pk_fma_f32 v[56:57], v[48:49], v[56:57], s[40:41] op_sel_hi:[1,1,0]
	v_pk_fma_f32 v[58:59], v[52:53], v[58:59], s[40:41] op_sel_hi:[1,1,0]
	v_pk_fma_f32 v[56:57], v[48:49], v[56:57], s[60:61] op_sel_hi:[1,1,0]
	v_pk_fma_f32 v[58:59], v[52:53], v[58:59], s[60:61] op_sel_hi:[1,1,0]
	v_pk_mul_f32 v[48:49], v[48:49], v[56:57]
	v_pk_mul_f32 v[52:53], v[52:53], v[58:59]
	v_pk_mul_f32 v[48:49], v[50:51], v[48:49]
	v_pk_mul_f32 v[50:51], v[54:55], v[52:53]
	v_pk_mul_f32 v[52:53], v[44:45], v[48:49]
	v_pk_fma_f32 v[48:49], v[44:45], v[48:49], v[44:45] neg_lo:[1,0,0] neg_hi:[1,0,0]
	v_cmp_gt_f32_e32 vcc, 0, v45
	v_pk_mul_f32 v[54:55], v[46:47], v[50:51]
	v_pk_fma_f32 v[50:51], v[46:47], v[50:51], v[46:47] neg_lo:[1,0,0] neg_hi:[1,0,0]
	v_cmp_gt_f32_e64 s[0:1], 0, v46
	v_cmp_gt_f32_e64 s[4:5], 0, v47
	v_cmp_gt_f32_e64 s[6:7], 0, v44
	v_cndmask_b32_e32 v45, v49, v53, vcc
	v_cndmask_b32_e64 v46, v50, v54, s[0:1]
	v_cndmask_b32_e64 v44, v48, v52, s[6:7]
	v_cndmask_b32_e64 v47, v51, v55, s[4:5]
	v_mul_f32_e32 v40, v40, v44
	v_mul_f32_e32 v41, v41, v45
	v_mul_f32_e32 v42, v42, v46
	v_mul_f32_e32 v43, v43, v47
	v_cvt_pk_bf16_f32 v40, v40, v41
	v_cvt_pk_bf16_f32 v41, v42, v43
	v_mov_b64_e32 v[42:43], v[166:167]
	s_nop 0
	global_store_dwordx2 v[90:91], v[40:41], off offset:320
	v_lshlrev_b32_e32 v40, 16, v42
	v_and_b32_e32 v41, 0xffff0000, v42
	v_lshlrev_b32_e32 v42, 16, v43
	v_and_b32_e32 v43, 0xffff0000, v43
	v_and_b32_e32 v45, 0x7fffffff, v41
	v_and_b32_e32 v44, 0x7fffffff, v40
	v_and_b32_e32 v49, 0x7fffffff, v43
	v_and_b32_e32 v48, 0x7fffffff, v42
	v_pk_fma_f32 v[44:45], v[44:45], s[12:13], 1.0 op_sel_hi:[1,0,0]
	v_pk_fma_f32 v[48:49], v[48:49], s[12:13], 1.0 op_sel_hi:[1,0,0]
	v_rcp_f32_e32 v44, v44
	v_rcp_f32_e32 v45, v45
	v_rcp_f32_e32 v48, v48
	v_rcp_f32_e32 v49, v49
	v_pk_mul_f32 v[46:47], v[40:41], v[40:41]
	v_pk_mul_f32 v[50:51], v[42:43], v[42:43]
	v_pk_mul_f32 v[46:47], v[46:47], s[62:63] op_sel_hi:[1,0]
	v_pk_mul_f32 v[50:51], v[50:51], s[62:63] op_sel_hi:[1,0]
	v_pk_fma_f32 v[52:53], v[44:45], s[36:37], v[88:89] op_sel_hi:[1,0,0]
	v_pk_fma_f32 v[54:55], v[48:49], s[36:37], v[88:89] op_sel_hi:[1,0,0]
	v_exp_f32_e32 v46, v46
	v_exp_f32_e32 v47, v47
	v_exp_f32_e32 v50, v50
	v_exp_f32_e32 v51, v51
	v_pk_fma_f32 v[52:53], v[44:45], v[52:53], s[38:39] op_sel_hi:[1,1,0]
	v_pk_fma_f32 v[54:55], v[48:49], v[54:55], s[38:39] op_sel_hi:[1,1,0]
	v_pk_fma_f32 v[52:53], v[44:45], v[52:53], s[40:41] op_sel_hi:[1,1,0]
	v_pk_fma_f32 v[54:55], v[48:49], v[54:55], s[40:41] op_sel_hi:[1,1,0]
	v_pk_fma_f32 v[52:53], v[44:45], v[52:53], s[60:61] op_sel_hi:[1,1,0]
	v_pk_fma_f32 v[54:55], v[48:49], v[54:55], s[60:61] op_sel_hi:[1,1,0]
	v_pk_mul_f32 v[44:45], v[44:45], v[52:53]
	v_pk_mul_f32 v[48:49], v[48:49], v[54:55]
	v_pk_mul_f32 v[44:45], v[46:47], v[44:45]
	v_pk_mul_f32 v[46:47], v[50:51], v[48:49]
	v_pk_mul_f32 v[48:49], v[40:41], v[44:45]
	v_pk_fma_f32 v[44:45], v[40:41], v[44:45], v[40:41] neg_lo:[1,0,0] neg_hi:[1,0,0]
	v_cmp_gt_f32_e32 vcc, 0, v41
	v_pk_mul_f32 v[50:51], v[42:43], v[46:47]
	v_pk_fma_f32 v[46:47], v[42:43], v[46:47], v[42:43] neg_lo:[1,0,0] neg_hi:[1,0,0]
	v_cmp_gt_f32_e64 s[0:1], 0, v42
	v_cmp_gt_f32_e64 s[4:5], 0, v43
	v_cmp_gt_f32_e64 s[6:7], 0, v40
	v_cndmask_b32_e32 v41, v45, v49, vcc
	v_cndmask_b32_e64 v42, v46, v50, s[0:1]
	v_cndmask_b32_e64 v40, v44, v48, s[6:7]
	v_cndmask_b32_e64 v43, v47, v51, s[4:5]
	v_mul_f32_e32 v36, v36, v40
	v_mul_f32_e32 v37, v37, v41
	v_mul_f32_e32 v38, v38, v42
	v_mul_f32_e32 v39, v39, v43
	v_cvt_pk_bf16_f32 v36, v36, v37
	v_cvt_pk_bf16_f32 v37, v38, v39
	v_mov_b64_e32 v[38:39], v[168:169]
	s_nop 0
	global_store_dwordx2 v[90:91], v[36:37], off offset:352
	v_lshlrev_b32_e32 v36, 16, v38
	v_and_b32_e32 v37, 0xffff0000, v38
	v_lshlrev_b32_e32 v38, 16, v39
	v_and_b32_e32 v39, 0xffff0000, v39
	v_and_b32_e32 v41, 0x7fffffff, v37
	v_and_b32_e32 v40, 0x7fffffff, v36
	v_and_b32_e32 v45, 0x7fffffff, v39
	v_and_b32_e32 v44, 0x7fffffff, v38
	v_pk_fma_f32 v[40:41], v[40:41], s[12:13], 1.0 op_sel_hi:[1,0,0]
	v_pk_fma_f32 v[44:45], v[44:45], s[12:13], 1.0 op_sel_hi:[1,0,0]
	v_rcp_f32_e32 v40, v40
	v_rcp_f32_e32 v41, v41
	v_rcp_f32_e32 v44, v44
	v_rcp_f32_e32 v45, v45
	v_pk_mul_f32 v[42:43], v[36:37], v[36:37]
	v_pk_mul_f32 v[46:47], v[38:39], v[38:39]
	v_pk_mul_f32 v[42:43], v[42:43], s[62:63] op_sel_hi:[1,0]
	v_pk_mul_f32 v[46:47], v[46:47], s[62:63] op_sel_hi:[1,0]
	v_pk_fma_f32 v[48:49], v[40:41], s[36:37], v[88:89] op_sel_hi:[1,0,0]
	v_pk_fma_f32 v[50:51], v[44:45], s[36:37], v[88:89] op_sel_hi:[1,0,0]
	v_exp_f32_e32 v42, v42
	v_exp_f32_e32 v43, v43
	v_exp_f32_e32 v46, v46
	v_exp_f32_e32 v47, v47
	v_pk_fma_f32 v[48:49], v[40:41], v[48:49], s[38:39] op_sel_hi:[1,1,0]
	v_pk_fma_f32 v[50:51], v[44:45], v[50:51], s[38:39] op_sel_hi:[1,1,0]
	v_pk_fma_f32 v[48:49], v[40:41], v[48:49], s[40:41] op_sel_hi:[1,1,0]
	v_pk_fma_f32 v[50:51], v[44:45], v[50:51], s[40:41] op_sel_hi:[1,1,0]
	v_pk_fma_f32 v[48:49], v[40:41], v[48:49], s[60:61] op_sel_hi:[1,1,0]
	v_pk_fma_f32 v[50:51], v[44:45], v[50:51], s[60:61] op_sel_hi:[1,1,0]
	v_pk_mul_f32 v[40:41], v[40:41], v[48:49]
	v_pk_mul_f32 v[44:45], v[44:45], v[50:51]
	v_pk_mul_f32 v[40:41], v[42:43], v[40:41]
	v_pk_mul_f32 v[42:43], v[46:47], v[44:45]
	v_pk_mul_f32 v[44:45], v[36:37], v[40:41]
	v_pk_fma_f32 v[40:41], v[36:37], v[40:41], v[36:37] neg_lo:[1,0,0] neg_hi:[1,0,0]
	v_cmp_gt_f32_e32 vcc, 0, v37
	v_pk_mul_f32 v[46:47], v[38:39], v[42:43]
	v_pk_fma_f32 v[42:43], v[38:39], v[42:43], v[38:39] neg_lo:[1,0,0] neg_hi:[1,0,0]
	v_cmp_gt_f32_e64 s[0:1], 0, v38
	v_cmp_gt_f32_e64 s[4:5], 0, v39
	v_cmp_gt_f32_e64 s[6:7], 0, v36
	v_cndmask_b32_e32 v37, v41, v45, vcc
	v_cndmask_b32_e64 v38, v42, v46, s[0:1]
	v_cndmask_b32_e64 v36, v40, v44, s[6:7]
	v_cndmask_b32_e64 v39, v43, v47, s[4:5]
	v_mul_f32_e32 v32, v32, v36
	v_mul_f32_e32 v33, v33, v37
	v_mul_f32_e32 v34, v34, v38
	v_mul_f32_e32 v35, v35, v39
	v_cvt_pk_bf16_f32 v32, v32, v33
	v_cvt_pk_bf16_f32 v33, v34, v35
	v_mov_b64_e32 v[34:35], v[170:171]
	s_nop 0
	global_store_dwordx2 v[90:91], v[32:33], off offset:384
	v_lshlrev_b32_e32 v32, 16, v34
	v_and_b32_e32 v33, 0xffff0000, v34
	v_lshlrev_b32_e32 v34, 16, v35
	v_and_b32_e32 v35, 0xffff0000, v35
	v_and_b32_e32 v37, 0x7fffffff, v33
	v_and_b32_e32 v36, 0x7fffffff, v32
	v_and_b32_e32 v41, 0x7fffffff, v35
	v_and_b32_e32 v40, 0x7fffffff, v34
	v_pk_fma_f32 v[36:37], v[36:37], s[12:13], 1.0 op_sel_hi:[1,0,0]
	v_pk_fma_f32 v[40:41], v[40:41], s[12:13], 1.0 op_sel_hi:[1,0,0]
	v_rcp_f32_e32 v36, v36
	v_rcp_f32_e32 v37, v37
	v_rcp_f32_e32 v40, v40
	v_rcp_f32_e32 v41, v41
	v_pk_mul_f32 v[38:39], v[32:33], v[32:33]
	v_pk_mul_f32 v[42:43], v[34:35], v[34:35]
	v_pk_mul_f32 v[38:39], v[38:39], s[62:63] op_sel_hi:[1,0]
	v_pk_mul_f32 v[42:43], v[42:43], s[62:63] op_sel_hi:[1,0]
	v_pk_fma_f32 v[44:45], v[36:37], s[36:37], v[88:89] op_sel_hi:[1,0,0]
	v_pk_fma_f32 v[46:47], v[40:41], s[36:37], v[88:89] op_sel_hi:[1,0,0]
	v_exp_f32_e32 v38, v38
	v_exp_f32_e32 v39, v39
	v_exp_f32_e32 v42, v42
	v_exp_f32_e32 v43, v43
	v_pk_fma_f32 v[44:45], v[36:37], v[44:45], s[38:39] op_sel_hi:[1,1,0]
	v_pk_fma_f32 v[46:47], v[40:41], v[46:47], s[38:39] op_sel_hi:[1,1,0]
	v_pk_fma_f32 v[44:45], v[36:37], v[44:45], s[40:41] op_sel_hi:[1,1,0]
	v_pk_fma_f32 v[46:47], v[40:41], v[46:47], s[40:41] op_sel_hi:[1,1,0]
	v_pk_fma_f32 v[44:45], v[36:37], v[44:45], s[60:61] op_sel_hi:[1,1,0]
	v_pk_fma_f32 v[46:47], v[40:41], v[46:47], s[60:61] op_sel_hi:[1,1,0]
	v_pk_mul_f32 v[36:37], v[36:37], v[44:45]
	v_pk_mul_f32 v[40:41], v[40:41], v[46:47]
	v_pk_mul_f32 v[36:37], v[38:39], v[36:37]
	v_pk_mul_f32 v[38:39], v[42:43], v[40:41]
	v_pk_mul_f32 v[40:41], v[32:33], v[36:37]
	v_pk_fma_f32 v[36:37], v[32:33], v[36:37], v[32:33] neg_lo:[1,0,0] neg_hi:[1,0,0]
	v_cmp_gt_f32_e32 vcc, 0, v33
	v_pk_mul_f32 v[42:43], v[34:35], v[38:39]
	v_pk_fma_f32 v[38:39], v[34:35], v[38:39], v[34:35] neg_lo:[1,0,0] neg_hi:[1,0,0]
	v_cmp_gt_f32_e64 s[0:1], 0, v34
	v_cmp_gt_f32_e64 s[4:5], 0, v35
	v_cmp_gt_f32_e64 s[6:7], 0, v32
	v_cndmask_b32_e32 v33, v37, v41, vcc
	v_cndmask_b32_e64 v34, v38, v42, s[0:1]
	v_cndmask_b32_e64 v32, v36, v40, s[6:7]
	v_cndmask_b32_e64 v35, v39, v43, s[4:5]
	v_mul_f32_e32 v28, v28, v32
	v_mul_f32_e32 v29, v29, v33
	v_mul_f32_e32 v30, v30, v34
	v_mul_f32_e32 v31, v31, v35
	v_cvt_pk_bf16_f32 v28, v28, v29
	v_cvt_pk_bf16_f32 v29, v30, v31
	v_mov_b64_e32 v[30:31], v[172:173]
	v_add_f32_e32 v36, v20, v113
	v_add_f32_e32 v37, v21, v113
	v_add_f32_e32 v38, v22, v113
	v_add_f32_e32 v39, v23, v113
	global_store_dwordx2 v[90:91], v[28:29], off offset:416
	v_lshlrev_b32_e32 v20, 16, v30
	v_and_b32_e32 v21, 0xffff0000, v30
	v_lshlrev_b32_e32 v22, 16, v31
	v_and_b32_e32 v23, 0xffff0000, v31
	v_and_b32_e32 v25, 0x7fffffff, v21
	v_and_b32_e32 v24, 0x7fffffff, v20
	v_and_b32_e32 v29, 0x7fffffff, v23
	v_and_b32_e32 v28, 0x7fffffff, v22
	v_pk_fma_f32 v[24:25], v[24:25], s[12:13], 1.0 op_sel_hi:[1,0,0]
	v_pk_fma_f32 v[28:29], v[28:29], s[12:13], 1.0 op_sel_hi:[1,0,0]
	v_rcp_f32_e32 v24, v24
	v_rcp_f32_e32 v25, v25
	v_rcp_f32_e32 v28, v28
	v_rcp_f32_e32 v29, v29
	v_pk_mul_f32 v[26:27], v[20:21], v[20:21]
	v_pk_mul_f32 v[30:31], v[22:23], v[22:23]
	v_pk_mul_f32 v[26:27], v[26:27], s[62:63] op_sel_hi:[1,0]
	v_pk_mul_f32 v[30:31], v[30:31], s[62:63] op_sel_hi:[1,0]
	v_pk_fma_f32 v[32:33], v[24:25], s[36:37], v[88:89] op_sel_hi:[1,0,0]
	v_pk_fma_f32 v[34:35], v[28:29], s[36:37], v[88:89] op_sel_hi:[1,0,0]
	v_exp_f32_e32 v26, v26
	v_exp_f32_e32 v27, v27
	v_exp_f32_e32 v30, v30
	v_exp_f32_e32 v31, v31
	v_pk_fma_f32 v[32:33], v[24:25], v[32:33], s[38:39] op_sel_hi:[1,1,0]
	v_pk_fma_f32 v[34:35], v[28:29], v[34:35], s[38:39] op_sel_hi:[1,1,0]
	v_pk_fma_f32 v[32:33], v[24:25], v[32:33], s[40:41] op_sel_hi:[1,1,0]
	v_pk_fma_f32 v[34:35], v[28:29], v[34:35], s[40:41] op_sel_hi:[1,1,0]
	v_pk_fma_f32 v[32:33], v[24:25], v[32:33], s[60:61] op_sel_hi:[1,1,0]
	v_pk_fma_f32 v[34:35], v[28:29], v[34:35], s[60:61] op_sel_hi:[1,1,0]
	v_pk_mul_f32 v[24:25], v[24:25], v[32:33]
	v_pk_mul_f32 v[28:29], v[28:29], v[34:35]
	v_pk_mul_f32 v[24:25], v[26:27], v[24:25]
	v_pk_mul_f32 v[26:27], v[30:31], v[28:29]
	v_pk_mul_f32 v[28:29], v[20:21], v[24:25]
	v_pk_fma_f32 v[24:25], v[20:21], v[24:25], v[20:21] neg_lo:[1,0,0] neg_hi:[1,0,0]
	v_cmp_gt_f32_e32 vcc, 0, v21
	v_pk_mul_f32 v[30:31], v[22:23], v[26:27]
	v_pk_fma_f32 v[26:27], v[22:23], v[26:27], v[22:23] neg_lo:[1,0,0] neg_hi:[1,0,0]
	v_cmp_gt_f32_e64 s[0:1], 0, v22
	v_cmp_gt_f32_e64 s[4:5], 0, v23
	v_cmp_gt_f32_e64 s[6:7], 0, v20
	v_cndmask_b32_e32 v21, v25, v29, vcc
	v_cndmask_b32_e64 v22, v26, v30, s[0:1]
	v_cndmask_b32_e64 v20, v24, v28, s[6:7]
	v_cndmask_b32_e64 v23, v27, v31, s[4:5]
	v_mul_f32_e32 v20, v36, v20
	v_mul_f32_e32 v21, v37, v21
	v_mul_f32_e32 v22, v38, v22
	v_mul_f32_e32 v23, v39, v23
	v_cvt_pk_bf16_f32 v20, v20, v21
	v_cvt_pk_bf16_f32 v21, v22, v23
	v_mov_b64_e32 v[22:23], v[174:175]
	s_add_i32 s13, s13, s30
	s_cmpk_lt_i32 s13, 0x200
	global_store_dwordx2 v[90:91], v[20:21], off offset:448
	v_lshlrev_b32_e32 v0, 16, v22
	v_and_b32_e32 v1, 0xffff0000, v22
	v_lshlrev_b32_e32 v2, 16, v23
	v_and_b32_e32 v3, 0xffff0000, v23
	v_and_b32_e32 v5, 0x7fffffff, v1
	v_and_b32_e32 v4, 0x7fffffff, v0
	v_and_b32_e32 v9, 0x7fffffff, v3
	v_and_b32_e32 v8, 0x7fffffff, v2
	v_pk_fma_f32 v[4:5], v[4:5], s[12:13], 1.0 op_sel_hi:[1,0,0]
	v_pk_fma_f32 v[8:9], v[8:9], s[12:13], 1.0 op_sel_hi:[1,0,0]
	v_rcp_f32_e32 v4, v4
	v_rcp_f32_e32 v5, v5
	v_rcp_f32_e32 v8, v8
	v_rcp_f32_e32 v9, v9
	v_pk_mul_f32 v[6:7], v[0:1], v[0:1]
	v_pk_mul_f32 v[10:11], v[2:3], v[2:3]
	v_pk_mul_f32 v[6:7], v[6:7], s[62:63] op_sel_hi:[1,0]
	v_pk_fma_f32 v[12:13], v[4:5], s[36:37], v[88:89] op_sel_hi:[1,0,0]
	v_pk_mul_f32 v[10:11], v[10:11], s[62:63] op_sel_hi:[1,0]
	v_exp_f32_e32 v6, v6
	v_exp_f32_e32 v7, v7
	v_pk_fma_f32 v[14:15], v[8:9], s[36:37], v[88:89] op_sel_hi:[1,0,0]
	v_pk_fma_f32 v[12:13], v[4:5], v[12:13], s[38:39] op_sel_hi:[1,1,0]
	v_exp_f32_e32 v10, v10
	v_exp_f32_e32 v11, v11
	v_pk_fma_f32 v[14:15], v[8:9], v[14:15], s[38:39] op_sel_hi:[1,1,0]
	v_pk_fma_f32 v[12:13], v[4:5], v[12:13], s[40:41] op_sel_hi:[1,1,0]
	v_pk_fma_f32 v[14:15], v[8:9], v[14:15], s[40:41] op_sel_hi:[1,1,0]
	v_pk_fma_f32 v[12:13], v[4:5], v[12:13], s[60:61] op_sel_hi:[1,1,0]
	v_pk_fma_f32 v[14:15], v[8:9], v[14:15], s[60:61] op_sel_hi:[1,1,0]
	v_pk_mul_f32 v[4:5], v[4:5], v[12:13]
	v_pk_mul_f32 v[8:9], v[8:9], v[14:15]
	v_pk_mul_f32 v[4:5], v[6:7], v[4:5]
	v_pk_mul_f32 v[6:7], v[10:11], v[8:9]
	v_pk_mul_f32 v[8:9], v[0:1], v[4:5]
	v_pk_fma_f32 v[4:5], v[0:1], v[4:5], v[0:1] neg_lo:[1,0,0] neg_hi:[1,0,0]
	v_cmp_gt_f32_e32 vcc, 0, v1
	v_cmp_gt_f32_e64 s[6:7], 0, v0
	v_pk_mul_f32 v[10:11], v[2:3], v[6:7]
	v_pk_fma_f32 v[6:7], v[2:3], v[6:7], v[2:3] neg_lo:[1,0,0] neg_hi:[1,0,0]
	v_cmp_gt_f32_e64 s[0:1], 0, v2
	v_cmp_gt_f32_e64 s[4:5], 0, v3
	v_cndmask_b32_e64 v0, v4, v8, s[6:7]
	v_cndmask_b32_e32 v1, v5, v9, vcc
	v_cndmask_b32_e64 v2, v6, v10, s[0:1]
	v_cndmask_b32_e64 v3, v7, v11, s[4:5]
	v_mul_f32_e32 v0, v16, v0
	v_mul_f32_e32 v1, v17, v1
	v_mul_f32_e32 v2, v18, v2
	v_mul_f32_e32 v3, v19, v3
	v_cvt_pk_bf16_f32 v0, v0, v1
	v_cvt_pk_bf16_f32 v1, v2, v3
	global_store_dwordx2 v[90:91], v[0:1], off offset:480
	s_cbranch_scc1 .LBB0_696

.LBB0_715:
	s_or_b64 exec, exec, s[8:9]
	v_cvt_f32_u32_e32 v4, v2
	s_waitcnt vmcnt(0)
	v_readfirstlane_b32 s3, v3
	v_sub_u32_e32 v3, 0, v2
	v_rcp_iflag_f32_e32 v4, v4
	v_add_u32_e32 v5, s3, v1
	v_mul_f32_e32 v4, 0x4f7ffffe, v4
	v_cvt_u32_f32_e32 v4, v4
	v_mul_lo_u32 v1, v3, v4
	v_mul_hi_u32 v1, v4, v1
	v_add_u32_e32 v1, v4, v1
	v_mul_hi_u32 v1, v5, v1
	v_mul_lo_u32 v3, v1, v2
	v_sub_u32_e32 v3, v5, v3
	v_add_u32_e32 v4, 1, v1
	v_cmp_ge_u32_e32 vcc, v3, v2
	s_nop 1
	v_cndmask_b32_e32 v1, v1, v4, vcc
	v_sub_u32_e32 v4, v3, v2
	v_cndmask_b32_e32 v3, v3, v4, vcc
	v_add_u32_e32 v4, 1, v1
	v_cmp_ge_u32_e32 vcc, v3, v2
	v_add_u32_e32 v3, 1, v5
	s_nop 0
	v_cndmask_b32_e32 v1, v1, v4, vcc
	v_mul_lo_u32 v4, v2, v1
	v_add_u32_e32 v2, v4, v2
	v_cmp_ne_u32_e32 vcc, v3, v2
	s_and_saveexec_b64 s[6:7], vcc
	s_xor_b64 s[6:7], exec, s[6:7]
	s_cbranch_execz .LBB0_729
	s_waitcnt lgkmcnt(0)
	v_add_u32_e32 v3, 1, v1
	v_mul_lo_u32 v3, v3, v0
	v_mov_b32_e32 v0, 0x67000
	global_load_dword v0, v0, s[28:29] offset:1024 sc1
	s_add_u32 s12, s28, 0x67400
	s_addc_u32 s13, s29, 0
	s_waitcnt vmcnt(0)
	v_cmp_lt_u32_e32 vcc, v0, v3
	s_and_saveexec_b64 s[8:9], vcc
	s_cbranch_execz .LBB0_728
	s_add_u32 s10, s28, 0x64200
	s_addc_u32 s11, s29, 0
	s_mov_b32 s3, 1
	s_mov_b64 s[36:37], 0
	v_mov_b32_e32 v0, 0
	s_branch .LBB0_719

.LBB0_721:
	global_load_dword v2, v0, s[12:13] sc1
	s_add_i32 s3, s3, 1
	s_mov_b64 s[42:43], -1
	s_waitcnt vmcnt(0)
	v_cmp_ge_u32_e32 vcc, v2, v3
	s_orn2_b64 s[40:41], vcc, exec
	s_branch .LBB0_718

.LBB0_732:
	s_or_b64 exec, exec, s[8:9]
	v_cvt_f32_u32_e32 v3, v0
	s_waitcnt vmcnt(0)
	v_readfirstlane_b32 s3, v2
	s_add_u32 s8, s28, 0x67500
	s_addc_u32 s9, s29, 0
	v_rcp_iflag_f32_e32 v3, v3
	v_add_u32_e32 v1, s3, v1
	v_add_u32_e32 v4, 1, v1
	s_mov_b64 s[10:11], -1
	v_mul_f32_e32 v2, 0x4f7ffffe, v3
	v_cvt_u32_f32_e32 v2, v2
	v_sub_u32_e32 v3, 0, v0
	v_mul_lo_u32 v3, v3, v2
	v_mul_hi_u32 v3, v2, v3
	v_add_u32_e32 v2, v2, v3
	v_mul_hi_u32 v2, v1, v2
	v_mul_lo_u32 v3, v2, v0
	v_sub_u32_e32 v1, v1, v3
	v_add_u32_e32 v5, 1, v2
	v_cmp_ge_u32_e32 vcc, v1, v0
	v_sub_u32_e32 v3, v1, v0
	s_nop 0
	v_cndmask_b32_e32 v2, v2, v5, vcc
	v_cndmask_b32_e32 v1, v1, v3, vcc
	v_add_u32_e32 v3, 1, v2
	v_cmp_ge_u32_e32 vcc, v1, v0
	s_nop 1
	v_cndmask_b32_e32 v2, v2, v3, vcc
	v_mul_lo_u32 v1, v0, v2
	v_add_u32_e32 v0, v1, v0
	v_cmp_ne_u32_e32 vcc, v4, v0
	v_mov_b32_e32 v5, v0
	v_mov_b64_e32 v[0:1], s[8:9]
	s_and_saveexec_b64 s[6:7], vcc
	s_cbranch_execz .LBB0_744
	v_mov_b32_e32 v0, 0
	global_load_dword v1, v0, s[8:9] offset:-256 sc1
	s_mov_b64 s[36:37], 0
	s_waitcnt vmcnt(0)
	v_cmp_lt_u32_e32 vcc, v1, v5
	s_and_saveexec_b64 s[12:13], vcc
	s_cbranch_execz .LBB0_743
	s_add_u32 s10, s28, 0x64200
	s_addc_u32 s11, s29, 0
	s_mov_b32 s3, 1
	s_branch .LBB0_736

.LBB0_738:
	global_load_dword v1, v0, s[8:9] offset:-256 sc1
	s_add_i32 s3, s3, 1
	s_mov_b64 s[40:41], -1
	s_waitcnt vmcnt(0)
	v_cmp_ge_u32_e32 vcc, v1, v5
	s_orn2_b64 s[60:61], vcc, exec
	s_branch .LBB0_735

.LBB0_942:
	global_load_dword v1, v0, s[8:9] offset:-256 sc1
	s_add_i32 s3, s3, 1
	s_mov_b64 s[40:41], -1
	s_waitcnt vmcnt(0)
	v_cmp_ge_u32_e32 vcc, v1, v5
	s_orn2_b64 s[52:53], vcc, exec
	s_branch .LBB0_939

.LBB0_986:
	s_or_b64 exec, exec, s[10:11]
	v_cvt_f32_u32_e32 v4, v2
	s_waitcnt vmcnt(0)
	v_readfirstlane_b32 s3, v3
	v_sub_u32_e32 v3, 0, v2
	v_rcp_iflag_f32_e32 v4, v4
	v_add_u32_e32 v5, s3, v1
	v_mul_f32_e32 v4, 0x4f7ffffe, v4
	v_cvt_u32_f32_e32 v4, v4
	v_mul_lo_u32 v1, v3, v4
	v_mul_hi_u32 v1, v4, v1
	v_add_u32_e32 v1, v4, v1
	v_mul_hi_u32 v1, v5, v1
	v_mul_lo_u32 v3, v1, v2
	v_sub_u32_e32 v3, v5, v3
	v_add_u32_e32 v4, 1, v1
	v_cmp_ge_u32_e32 vcc, v3, v2
	s_nop 1
	v_cndmask_b32_e32 v1, v1, v4, vcc
	v_sub_u32_e32 v4, v3, v2
	v_cndmask_b32_e32 v3, v3, v4, vcc
	v_add_u32_e32 v4, 1, v1
	v_cmp_ge_u32_e32 vcc, v3, v2
	v_add_u32_e32 v3, 1, v5
	s_nop 0
	v_cndmask_b32_e32 v1, v1, v4, vcc
	v_mul_lo_u32 v4, v2, v1
	v_add_u32_e32 v2, v4, v2
	v_cmp_ne_u32_e32 vcc, v3, v2
	s_and_saveexec_b64 s[8:9], vcc
	s_xor_b64 s[8:9], exec, s[8:9]
	s_cbranch_execz .LBB0_1000
	s_waitcnt lgkmcnt(0)
	v_add_u32_e32 v3, 1, v1
	v_mul_lo_u32 v3, v3, v0
	v_mov_b32_e32 v0, 0x67000
	global_load_dword v0, v0, s[28:29] offset:1024 sc1
	s_add_u32 s14, s28, 0x67400
	s_addc_u32 s15, s29, 0
	s_waitcnt vmcnt(0)
	v_cmp_lt_u32_e32 vcc, v0, v3
	s_and_saveexec_b64 s[10:11], vcc
	s_cbranch_execz .LBB0_999
	s_add_u32 s12, s28, 0x64200
	s_addc_u32 s13, s29, 0
	s_mov_b32 s3, 1
	s_mov_b64 s[40:41], 0
	v_mov_b32_e32 v0, 0
	s_branch .LBB0_990

.LBB0_992:
	global_load_dword v2, v0, s[14:15] sc1
	s_add_i32 s3, s3, 1
	s_mov_b64 s[54:55], -1
	s_waitcnt vmcnt(0)
	v_cmp_ge_u32_e32 vcc, v2, v3
	s_orn2_b64 s[52:53], vcc, exec
	s_branch .LBB0_989

.LBB0_1003:
	s_or_b64 exec, exec, s[10:11]
	v_cvt_f32_u32_e32 v3, v0
	s_waitcnt vmcnt(0)
	v_readfirstlane_b32 s3, v2
	s_add_u32 s10, s28, 0x67500
	s_addc_u32 s11, s29, 0
	v_rcp_iflag_f32_e32 v3, v3
	v_add_u32_e32 v1, s3, v1
	v_add_u32_e32 v4, 1, v1
	s_mov_b64 s[12:13], -1
	v_mul_f32_e32 v2, 0x4f7ffffe, v3
	v_cvt_u32_f32_e32 v2, v2
	v_sub_u32_e32 v3, 0, v0
	v_mul_lo_u32 v3, v3, v2
	v_mul_hi_u32 v3, v2, v3
	v_add_u32_e32 v2, v2, v3
	v_mul_hi_u32 v2, v1, v2
	v_mul_lo_u32 v3, v2, v0
	v_sub_u32_e32 v1, v1, v3
	v_add_u32_e32 v5, 1, v2
	v_cmp_ge_u32_e32 vcc, v1, v0
	v_sub_u32_e32 v3, v1, v0
	s_nop 0
	v_cndmask_b32_e32 v2, v2, v5, vcc
	v_cndmask_b32_e32 v1, v1, v3, vcc
	v_add_u32_e32 v3, 1, v2
	v_cmp_ge_u32_e32 vcc, v1, v0
	s_nop 1
	v_cndmask_b32_e32 v2, v2, v3, vcc
	v_mul_lo_u32 v1, v0, v2
	v_add_u32_e32 v0, v1, v0
	v_cmp_ne_u32_e32 vcc, v4, v0
	v_mov_b32_e32 v5, v0
	v_mov_b64_e32 v[0:1], s[10:11]
	s_and_saveexec_b64 s[8:9], vcc
	s_cbranch_execz .LBB0_1015
	v_mov_b32_e32 v0, 0
	global_load_dword v1, v0, s[10:11] offset:-256 sc1
	s_mov_b64 s[40:41], 0
	s_waitcnt vmcnt(0)
	v_cmp_lt_u32_e32 vcc, v1, v5
	s_and_saveexec_b64 s[14:15], vcc
	s_cbranch_execz .LBB0_1014
	s_add_u32 s12, s28, 0x64200
	s_addc_u32 s13, s29, 0
	s_mov_b32 s3, 1
	s_branch .LBB0_1007

.LBB0_1009:
	global_load_dword v1, v0, s[10:11] offset:-256 sc1
	s_add_i32 s3, s3, 1
	s_mov_b64 s[52:53], -1
	s_waitcnt vmcnt(0)
	v_cmp_ge_u32_e32 vcc, v1, v5
	s_orn2_b64 s[58:59], vcc, exec
	s_branch .LBB0_1006

.LBB0_1041:
	s_or_b64 exec, exec, s[10:11]
	v_cvt_f32_u32_e32 v4, v2
	s_waitcnt vmcnt(0)
	v_readfirstlane_b32 s3, v3
	v_sub_u32_e32 v3, 0, v2
	v_rcp_iflag_f32_e32 v4, v4
	v_add_u32_e32 v5, s3, v1
	v_mul_f32_e32 v4, 0x4f7ffffe, v4
	v_cvt_u32_f32_e32 v4, v4
	v_mul_lo_u32 v1, v3, v4
	v_mul_hi_u32 v1, v4, v1
	v_add_u32_e32 v1, v4, v1
	v_mul_hi_u32 v1, v5, v1
	v_mul_lo_u32 v3, v1, v2
	v_sub_u32_e32 v3, v5, v3
	v_add_u32_e32 v4, 1, v1
	v_cmp_ge_u32_e32 vcc, v3, v2
	s_nop 1
	v_cndmask_b32_e32 v1, v1, v4, vcc
	v_sub_u32_e32 v4, v3, v2
	v_cndmask_b32_e32 v3, v3, v4, vcc
	v_add_u32_e32 v4, 1, v1
	v_cmp_ge_u32_e32 vcc, v3, v2
	v_add_u32_e32 v3, 1, v5
	s_nop 0
	v_cndmask_b32_e32 v1, v1, v4, vcc
	v_mul_lo_u32 v4, v2, v1
	v_add_u32_e32 v2, v4, v2
	v_cmp_ne_u32_e32 vcc, v3, v2
	s_and_saveexec_b64 s[8:9], vcc
	s_xor_b64 s[8:9], exec, s[8:9]
	s_cbranch_execz .LBB0_1055
	s_waitcnt lgkmcnt(0)
	v_add_u32_e32 v3, 1, v1
	v_mul_lo_u32 v3, v3, v0
	v_mov_b32_e32 v0, 0x67000
	global_load_dword v0, v0, s[28:29] offset:1024 sc1
	s_add_u32 s14, s28, 0x67400
	s_addc_u32 s15, s29, 0
	s_waitcnt vmcnt(0)
	v_cmp_lt_u32_e32 vcc, v0, v3
	s_and_saveexec_b64 s[10:11], vcc
	s_cbranch_execz .LBB0_1054
	s_add_u32 s12, s28, 0x64200
	s_addc_u32 s13, s29, 0
	s_mov_b32 s3, 1
	s_mov_b64 s[16:17], 0
	v_mov_b32_e32 v0, 0
	s_branch .LBB0_1045

.LBB0_1047:
	global_load_dword v2, v0, s[14:15] sc1
	s_add_i32 s3, s3, 1
	s_mov_b64 s[52:53], -1
	s_waitcnt vmcnt(0)
	v_cmp_ge_u32_e32 vcc, v2, v3
	s_orn2_b64 s[42:43], vcc, exec
	s_branch .LBB0_1044

.LBB0_1058:
	s_or_b64 exec, exec, s[10:11]
	v_cvt_f32_u32_e32 v3, v0
	s_waitcnt vmcnt(0)
	v_readfirstlane_b32 s3, v2
	s_add_u32 s10, s28, 0x67500
	s_addc_u32 s11, s29, 0
	v_rcp_iflag_f32_e32 v3, v3
	v_add_u32_e32 v1, s3, v1
	v_add_u32_e32 v4, 1, v1
	s_mov_b64 s[12:13], -1
	v_mul_f32_e32 v2, 0x4f7ffffe, v3
	v_cvt_u32_f32_e32 v2, v2
	v_sub_u32_e32 v3, 0, v0
	v_mul_lo_u32 v3, v3, v2
	v_mul_hi_u32 v3, v2, v3
	v_add_u32_e32 v2, v2, v3
	v_mul_hi_u32 v2, v1, v2
	v_mul_lo_u32 v3, v2, v0
	v_sub_u32_e32 v1, v1, v3
	v_add_u32_e32 v5, 1, v2
	v_cmp_ge_u32_e32 vcc, v1, v0
	v_sub_u32_e32 v3, v1, v0
	s_nop 0
	v_cndmask_b32_e32 v2, v2, v5, vcc
	v_cndmask_b32_e32 v1, v1, v3, vcc
	v_add_u32_e32 v3, 1, v2
	v_cmp_ge_u32_e32 vcc, v1, v0
	s_nop 1
	v_cndmask_b32_e32 v2, v2, v3, vcc
	v_mul_lo_u32 v1, v0, v2
	v_add_u32_e32 v0, v1, v0
	v_cmp_ne_u32_e32 vcc, v4, v0
	v_mov_b32_e32 v5, v0
	v_mov_b64_e32 v[0:1], s[10:11]
	s_and_saveexec_b64 s[8:9], vcc
	s_cbranch_execz .LBB0_1070
	v_mov_b32_e32 v0, 0
	global_load_dword v1, v0, s[10:11] offset:-256 sc1
	s_mov_b64 s[16:17], 0
	s_waitcnt vmcnt(0)
	v_cmp_lt_u32_e32 vcc, v1, v5
	s_and_saveexec_b64 s[14:15], vcc
	s_cbranch_execz .LBB0_1069
	s_add_u32 s12, s28, 0x64200
	s_addc_u32 s13, s29, 0
	s_mov_b32 s3, 1
	s_branch .LBB0_1062

.LBB0_1064:
	global_load_dword v1, v0, s[10:11] offset:-256 sc1
	s_add_i32 s3, s3, 1
	s_mov_b64 s[42:43], -1
	s_waitcnt vmcnt(0)
	v_cmp_ge_u32_e32 vcc, v1, v5
	s_orn2_b64 s[54:55], vcc, exec
	s_branch .LBB0_1061

.LBB0_1130:
	global_load_dword v2, v0, s[12:13] sc1
	s_add_i32 s3, s3, 1
	s_mov_b64 s[40:41], -1
	s_waitcnt vmcnt(0)
	v_cmp_ge_u32_e32 vcc, v2, v3
	s_orn2_b64 s[38:39], vcc, exec
	s_branch .LBB0_1127

.LBB0_1147:
	global_load_dword v1, v0, s[8:9] offset:-256 sc1
	s_add_i32 s3, s3, 1
	s_mov_b64 s[38:39], -1
	s_waitcnt vmcnt(0)
	v_cmp_ge_u32_e32 vcc, v1, v5
	s_orn2_b64 s[42:43], vcc, exec
	s_branch .LBB0_1144

.LBB0_1300:
	global_load_dword v2, v0, s[14:15] sc1
	s_add_i32 s3, s3, 1
	s_mov_b64 s[40:41], -1
	s_waitcnt vmcnt(0)
	v_cmp_ge_u32_e32 vcc, v2, v3
	s_orn2_b64 s[38:39], vcc, exec
	s_branch .LBB0_1297

.LBB0_1317:
	global_load_dword v1, v0, s[10:11] offset:-256 sc1
	s_add_i32 s3, s3, 1
	s_mov_b64 s[38:39], -1
	s_waitcnt vmcnt(0)
	v_cmp_ge_u32_e32 vcc, v1, v5
	s_orn2_b64 s[42:43], vcc, exec
	s_branch .LBB0_1314

.LBB0_1368:
	global_load_dword v2, v0, s[12:13] sc1
	s_add_i32 s3, s3, 1
	s_mov_b64 s[34:35], -1
	s_waitcnt vmcnt(0)
	v_cmp_ge_u32_e32 vcc, v2, v3
	s_orn2_b64 s[18:19], vcc, exec
	s_branch .LBB0_1365

.LBB0_1385:
	global_load_dword v1, v0, s[8:9] offset:-256 sc1
	s_add_i32 s3, s3, 1
	s_mov_b64 s[18:19], -1
	s_waitcnt vmcnt(0)
	v_cmp_ge_u32_e32 vcc, v1, v5
	s_orn2_b64 s[36:37], vcc, exec
	s_branch .LBB0_1382
